# K-loop LDS-DMA loads in saddr form: 64-bit VALU address adds replaced by SALU base sums, dead high-half moves removed (all four GEMMs)
# baseline (speedup 1.0000x reference)
.LBB0_60:
	s_ashr_i32 s21, s20, 31
	s_lshl_b64 s[4:5], s[20:21], 19
	s_add_u32 s24, s66, s4
	s_addc_u32 s25, s67, s5
	s_and_b64 s[4:5], s[22:23], exec
	s_cselect_b32 s21, s25, s1
	s_cselect_b32 s27, s24, s0
	s_lshl_b32 s29, s52, 8
	s_or_b32 s30, s29, 0x80
	s_add_u32 s31, s0, 0x100
	s_addc_u32 s53, s1, 0
	s_mov_b32 s54, -2
	s_mov_b64 s[0:1], 0
	ds_read_b128 v[144:147], v178
	ds_read_b128 v[148:151], v178 offset:1024
	ds_read_b128 v[152:155], v178 offset:2048
	ds_read_b128 v[156:159], v178 offset:3072
	ds_read_b128 v[128:131], v179
	ds_read_b128 v[132:135], v179 offset:1024
	ds_read_b128 v[136:139], v179 offset:2048
	ds_read_b128 v[140:143], v179 offset:3072
	s_cmp_eq_u32 s54, 12
	s_cselect_b64 s[6:7], -1, 0
	s_add_u32 s4, s47, s0
	s_addc_u32 s5, s48, s1
	s_mov_b32 m0, s49
	ds_read_b128 v[190:193], v180
	ds_read_b128 v[194:197], v180 offset:1024
	ds_read_b128 v[198:201], v180 offset:2048
	ds_read_b128 v[202:205], v180 offset:3072
	ds_read_b128 v[206:209], v180 offset:4096
	ds_read_b128 v[210:213], v180 offset:5120
	ds_read_b128 v[214:217], v180 offset:6144
	ds_read_b128 v[218:221], v180 offset:7168
	global_load_lds_dwordx4 v168, s[4:5]
	s_mov_b32 m0, s50
	s_nop 0
	global_load_lds_dwordx4 v170, s[4:5]
	s_waitcnt vmcnt(8)
	s_waitcnt lgkmcnt(0)
	s_barrier
	s_setprio 1
	s_waitcnt lgkmcnt(0)
	v_mfma_f32_16x16x32_bf16 v[124:127], v[144:147], v[190:193], 0
	v_mfma_f32_16x16x32_bf16 v[120:123], v[152:155], v[190:193], 0
	v_mfma_f32_16x16x32_bf16 v[108:111], v[144:147], v[198:201], 0
	v_mfma_f32_16x16x32_bf16 v[104:107], v[152:155], v[198:201], 0
	v_mfma_f32_16x16x32_bf16 v[92:95], v[144:147], v[206:209], 0
	v_mfma_f32_16x16x32_bf16 v[88:91], v[152:155], v[206:209], 0
	v_mfma_f32_16x16x32_bf16 v[76:79], v[144:147], v[214:217], 0
	v_mfma_f32_16x16x32_bf16 v[72:75], v[152:155], v[214:217], 0
	v_mfma_f32_16x16x32_bf16 v[124:127], v[148:151], v[194:197], v[124:127]
	v_mfma_f32_16x16x32_bf16 v[120:123], v[156:159], v[194:197], v[120:123]
	v_mfma_f32_16x16x32_bf16 v[108:111], v[148:151], v[202:205], v[108:111]
	v_mfma_f32_16x16x32_bf16 v[104:107], v[156:159], v[202:205], v[104:107]
	v_mfma_f32_16x16x32_bf16 v[92:95], v[148:151], v[210:213], v[92:95]
	v_mfma_f32_16x16x32_bf16 v[88:91], v[156:159], v[210:213], v[88:91]
	v_mfma_f32_16x16x32_bf16 v[76:79], v[148:151], v[218:221], v[76:79]
	v_mfma_f32_16x16x32_bf16 v[72:75], v[156:159], v[218:221], v[72:75]
	v_mfma_f32_16x16x32_bf16 v[116:119], v[128:131], v[190:193], 0
	v_mfma_f32_16x16x32_bf16 v[112:115], v[136:139], v[190:193], 0
	v_mfma_f32_16x16x32_bf16 v[100:103], v[128:131], v[198:201], 0
	v_mfma_f32_16x16x32_bf16 v[96:99], v[136:139], v[198:201], 0
	v_mfma_f32_16x16x32_bf16 v[84:87], v[128:131], v[206:209], 0
	v_mfma_f32_16x16x32_bf16 v[80:83], v[136:139], v[206:209], 0
	v_mfma_f32_16x16x32_bf16 v[68:71], v[128:131], v[214:217], 0
	v_mfma_f32_16x16x32_bf16 v[64:67], v[136:139], v[214:217], 0
	v_mfma_f32_16x16x32_bf16 v[116:119], v[132:135], v[194:197], v[116:119]
	v_mfma_f32_16x16x32_bf16 v[112:115], v[140:143], v[194:197], v[112:115]
	v_mfma_f32_16x16x32_bf16 v[100:103], v[132:135], v[202:205], v[100:103]
	v_mfma_f32_16x16x32_bf16 v[96:99], v[140:143], v[202:205], v[96:99]
	v_mfma_f32_16x16x32_bf16 v[84:87], v[132:135], v[210:213], v[84:87]
	v_mfma_f32_16x16x32_bf16 v[80:83], v[140:143], v[210:213], v[80:83]
	v_mfma_f32_16x16x32_bf16 v[68:71], v[132:135], v[218:221], v[68:71]
	v_mfma_f32_16x16x32_bf16 v[64:67], v[140:143], v[218:221], v[64:67]
	s_setprio 0
	s_barrier
	s_and_b64 s[4:5], s[22:23], s[6:7]
	s_andn2_b64 vcc, exec, s[4:5]
	s_cbranch_vccnz .Lpk0_LBB0_63
	s_lshl_b32 s57, s29, 11
	s_lshl_b32 s58, s30, 11
	v_add_u32_e32 v164, s57, v247
	v_add_u32_e32 v168, s58, v247
	v_add_u32_e32 v166, 0x20000, v164
	v_add_u32_e32 v170, 0x20000, v168
	s_branch .Lpk0_LBB0_64
.Lpk0_LBB0_63:
.Lpk0_LBB0_64:
	s_add_u32 s4, s0, 0x100
	s_addc_u32 s5, s1, 0
	s_and_b64 s[56:57], s[6:7], exec
	s_cselect_b32 s8, 0, s4
	s_add_u32 s55, s31, s0
	s_addc_u32 s56, s53, s1
	s_and_b64 s[0:1], s[6:7], exec
	s_cselect_b32 s1, s21, s56
	s_cselect_b32 s0, s27, s55
	s_add_u32 s98, s2, s8
	s_addc_u32 s99, s3, s9
	s_mov_b32 m0, s35
	s_add_u32 s6, s0, 0x40000
	ds_read_b128 v[190:193], v180 offset:16384
	ds_read_b128 v[194:197], v180 offset:17408
	ds_read_b128 v[198:201], v180 offset:18432
	ds_read_b128 v[202:205], v180 offset:19456
	ds_read_b128 v[206:209], v180 offset:20480
	ds_read_b128 v[210:213], v180 offset:21504
	ds_read_b128 v[214:217], v180 offset:22528
	ds_read_b128 v[218:221], v180 offset:23552
	global_load_lds_dwordx4 v160, s[0:1]
	s_mov_b32 m0, s36
	s_addc_u32 s7, s1, 0
	global_load_lds_dwordx4 v162, s[0:1]
	s_mov_b32 m0, s37
	s_nop 0
	global_load_lds_dwordx4 v160, s[6:7]
	s_mov_b32 m0, s38
	s_nop 0
	global_load_lds_dwordx4 v162, s[6:7]
	s_mov_b32 m0, s34
	s_nop 0
	global_load_lds_dwordx4 v164, s[98:99]
	s_mov_b32 m0, s39
	s_nop 0
	global_load_lds_dwordx4 v166, s[98:99]
	s_waitcnt vmcnt(8)
	s_waitcnt lgkmcnt(0)
	s_barrier
	s_setprio 1
	s_waitcnt lgkmcnt(0)
	v_mfma_f32_16x16x32_bf16 v[60:63], v[144:147], v[190:193], 0
	v_mfma_f32_16x16x32_bf16 v[56:59], v[152:155], v[190:193], 0
	v_mfma_f32_16x16x32_bf16 v[44:47], v[144:147], v[198:201], 0
	v_mfma_f32_16x16x32_bf16 v[40:43], v[152:155], v[198:201], 0
	v_mfma_f32_16x16x32_bf16 v[28:31], v[144:147], v[206:209], 0
	v_mfma_f32_16x16x32_bf16 v[24:27], v[152:155], v[206:209], 0
	v_mfma_f32_16x16x32_bf16 v[12:15], v[144:147], v[214:217], 0
	v_mfma_f32_16x16x32_bf16 v[8:11], v[152:155], v[214:217], 0
	v_mfma_f32_16x16x32_bf16 v[60:63], v[148:151], v[194:197], v[60:63]
	v_mfma_f32_16x16x32_bf16 v[56:59], v[156:159], v[194:197], v[56:59]
	v_mfma_f32_16x16x32_bf16 v[44:47], v[148:151], v[202:205], v[44:47]
	v_mfma_f32_16x16x32_bf16 v[40:43], v[156:159], v[202:205], v[40:43]
	v_mfma_f32_16x16x32_bf16 v[28:31], v[148:151], v[210:213], v[28:31]
	v_mfma_f32_16x16x32_bf16 v[24:27], v[156:159], v[210:213], v[24:27]
	v_mfma_f32_16x16x32_bf16 v[12:15], v[148:151], v[218:221], v[12:15]
	v_mfma_f32_16x16x32_bf16 v[8:11], v[156:159], v[218:221], v[8:11]
	v_mfma_f32_16x16x32_bf16 v[52:55], v[128:131], v[190:193], 0
	v_mfma_f32_16x16x32_bf16 v[48:51], v[136:139], v[190:193], 0
	v_mfma_f32_16x16x32_bf16 v[36:39], v[128:131], v[198:201], 0
	v_mfma_f32_16x16x32_bf16 v[32:35], v[136:139], v[198:201], 0
	v_mfma_f32_16x16x32_bf16 v[20:23], v[128:131], v[206:209], 0
	v_mfma_f32_16x16x32_bf16 v[16:19], v[136:139], v[206:209], 0
	v_mfma_f32_16x16x32_bf16 v[4:7], v[128:131], v[214:217], 0
	v_mfma_f32_16x16x32_bf16 v[0:3], v[136:139], v[214:217], 0
	v_mfma_f32_16x16x32_bf16 v[52:55], v[132:135], v[194:197], v[52:55]
	v_mfma_f32_16x16x32_bf16 v[48:51], v[140:143], v[194:197], v[48:51]
	v_mfma_f32_16x16x32_bf16 v[36:39], v[132:135], v[202:205], v[36:39]
	v_mfma_f32_16x16x32_bf16 v[32:35], v[140:143], v[202:205], v[32:35]
	v_mfma_f32_16x16x32_bf16 v[20:23], v[132:135], v[210:213], v[20:23]
	v_mfma_f32_16x16x32_bf16 v[16:19], v[140:143], v[210:213], v[16:19]
	v_mfma_f32_16x16x32_bf16 v[4:7], v[132:135], v[218:221], v[4:7]
	v_mfma_f32_16x16x32_bf16 v[0:3], v[140:143], v[218:221], v[0:3]
	s_setprio 0
	s_barrier
	s_add_i32 s6, 0, 0x18000
	s_add_i32 s7, 0, 0x1c000
	v_add_u32_e32 v140, s6, v176
	v_add_u32_e32 v156, s7, v176
	ds_read_b128 v[128:131], v140
	ds_read_b128 v[132:135], v140 offset:1024
	ds_read_b128 v[136:139], v140 offset:2048
	ds_read_b128 v[140:143], v140 offset:3072
	ds_read_b128 v[144:147], v156
	ds_read_b128 v[148:151], v156 offset:1024
	ds_read_b128 v[152:155], v156 offset:2048
	ds_read_b128 v[156:159], v156 offset:3072
	s_mov_b32 m0, s40
	ds_read_b128 v[190:193], v180 offset:32768
	ds_read_b128 v[194:197], v180 offset:33792
	ds_read_b128 v[198:201], v180 offset:34816
	ds_read_b128 v[202:205], v180 offset:35840
	ds_read_b128 v[206:209], v180 offset:36864
	ds_read_b128 v[210:213], v180 offset:37888
	ds_read_b128 v[214:217], v180 offset:38912
	ds_read_b128 v[218:221], v180 offset:39936
	global_load_lds_dwordx4 v168, s[98:99]
	s_mov_b32 m0, s41
	s_nop 0
	global_load_lds_dwordx4 v170, s[98:99]
	s_waitcnt vmcnt(8)
	s_waitcnt lgkmcnt(0)
	s_barrier
	s_setprio 1
	s_waitcnt lgkmcnt(0)
	v_mfma_f32_16x16x32_bf16 v[124:127], v[128:131], v[190:193], v[124:127]
	v_mfma_f32_16x16x32_bf16 v[120:123], v[136:139], v[190:193], v[120:123]
	v_mfma_f32_16x16x32_bf16 v[108:111], v[128:131], v[198:201], v[108:111]
	v_mfma_f32_16x16x32_bf16 v[104:107], v[136:139], v[198:201], v[104:107]
	v_mfma_f32_16x16x32_bf16 v[92:95], v[128:131], v[206:209], v[92:95]
	v_mfma_f32_16x16x32_bf16 v[88:91], v[136:139], v[206:209], v[88:91]
	v_mfma_f32_16x16x32_bf16 v[76:79], v[128:131], v[214:217], v[76:79]
	v_mfma_f32_16x16x32_bf16 v[72:75], v[136:139], v[214:217], v[72:75]
	v_mfma_f32_16x16x32_bf16 v[124:127], v[132:135], v[194:197], v[124:127]
	v_mfma_f32_16x16x32_bf16 v[120:123], v[140:143], v[194:197], v[120:123]
	v_mfma_f32_16x16x32_bf16 v[108:111], v[132:135], v[202:205], v[108:111]
	v_mfma_f32_16x16x32_bf16 v[104:107], v[140:143], v[202:205], v[104:107]
	v_mfma_f32_16x16x32_bf16 v[92:95], v[132:135], v[210:213], v[92:95]
	v_mfma_f32_16x16x32_bf16 v[88:91], v[140:143], v[210:213], v[88:91]
	v_mfma_f32_16x16x32_bf16 v[76:79], v[132:135], v[218:221], v[76:79]
	v_mfma_f32_16x16x32_bf16 v[72:75], v[140:143], v[218:221], v[72:75]
	v_mfma_f32_16x16x32_bf16 v[116:119], v[144:147], v[190:193], v[116:119]
	v_mfma_f32_16x16x32_bf16 v[112:115], v[152:155], v[190:193], v[112:115]
	v_mfma_f32_16x16x32_bf16 v[100:103], v[144:147], v[198:201], v[100:103]
	v_mfma_f32_16x16x32_bf16 v[96:99], v[152:155], v[198:201], v[96:99]
	v_mfma_f32_16x16x32_bf16 v[84:87], v[144:147], v[206:209], v[84:87]
	v_mfma_f32_16x16x32_bf16 v[80:83], v[152:155], v[206:209], v[80:83]
	v_mfma_f32_16x16x32_bf16 v[68:71], v[144:147], v[214:217], v[68:71]
	v_mfma_f32_16x16x32_bf16 v[64:67], v[152:155], v[214:217], v[64:67]
	v_mfma_f32_16x16x32_bf16 v[116:119], v[148:151], v[194:197], v[116:119]
	v_mfma_f32_16x16x32_bf16 v[112:115], v[156:159], v[194:197], v[112:115]
	v_mfma_f32_16x16x32_bf16 v[100:103], v[148:151], v[202:205], v[100:103]
	v_mfma_f32_16x16x32_bf16 v[96:99], v[156:159], v[202:205], v[96:99]
	v_mfma_f32_16x16x32_bf16 v[84:87], v[148:151], v[210:213], v[84:87]
	v_mfma_f32_16x16x32_bf16 v[80:83], v[156:159], v[210:213], v[80:83]
	v_mfma_f32_16x16x32_bf16 v[68:71], v[148:151], v[218:221], v[68:71]
	v_mfma_f32_16x16x32_bf16 v[64:67], v[156:159], v[218:221], v[64:67]
	s_setprio 0
	s_barrier
	s_add_i32 s6, s6, s84
	s_add_u32 s100, s0, s14
	s_addc_u32 s101, s1, s15
	s_add_u32 s98, s98, s14
	s_addc_u32 s99, s99, s15
	s_mov_b32 m0, s6
	ds_read_b128 v[190:193], v180 offset:49152
	ds_read_b128 v[194:197], v180 offset:50176
	ds_read_b128 v[198:201], v180 offset:51200
	ds_read_b128 v[202:205], v180 offset:52224
	ds_read_b128 v[206:209], v180 offset:53248
	ds_read_b128 v[210:213], v180 offset:54272
	ds_read_b128 v[214:217], v180 offset:55296
	ds_read_b128 v[218:221], v180 offset:56320
	global_load_lds_dwordx4 v160, s[100:101]
	s_add_i32 m0, s6, 0x2000
	s_add_u32 s0, s0, 0x40080
	s_addc_u32 s1, s1, 0
	s_add_i32 s6, s7, s84
	global_load_lds_dwordx4 v162, s[100:101]
	s_mov_b32 m0, s6
	s_nop 0
	global_load_lds_dwordx4 v160, s[0:1]
	s_add_i32 m0, s6, 0x2000
	s_nop 0
	global_load_lds_dwordx4 v162, s[0:1]
	s_mov_b32 m0, s42
	s_nop 0
	global_load_lds_dwordx4 v164, s[98:99]
	s_mov_b32 m0, s43
	s_nop 0
	global_load_lds_dwordx4 v166, s[98:99]
	s_waitcnt vmcnt(8)
	s_waitcnt lgkmcnt(0)
	s_barrier
	s_setprio 1
	s_waitcnt lgkmcnt(0)
	v_mfma_f32_16x16x32_bf16 v[60:63], v[128:131], v[190:193], v[60:63]
	v_mfma_f32_16x16x32_bf16 v[56:59], v[136:139], v[190:193], v[56:59]
	v_mfma_f32_16x16x32_bf16 v[44:47], v[128:131], v[198:201], v[44:47]
	v_mfma_f32_16x16x32_bf16 v[40:43], v[136:139], v[198:201], v[40:43]
	v_mfma_f32_16x16x32_bf16 v[28:31], v[128:131], v[206:209], v[28:31]
	v_mfma_f32_16x16x32_bf16 v[24:27], v[136:139], v[206:209], v[24:27]
	v_mfma_f32_16x16x32_bf16 v[12:15], v[128:131], v[214:217], v[12:15]
	v_mfma_f32_16x16x32_bf16 v[8:11], v[136:139], v[214:217], v[8:11]
	v_mfma_f32_16x16x32_bf16 v[60:63], v[132:135], v[194:197], v[60:63]
	v_mfma_f32_16x16x32_bf16 v[56:59], v[140:143], v[194:197], v[56:59]
	v_mfma_f32_16x16x32_bf16 v[44:47], v[132:135], v[202:205], v[44:47]
	v_mfma_f32_16x16x32_bf16 v[40:43], v[140:143], v[202:205], v[40:43]
	v_mfma_f32_16x16x32_bf16 v[28:31], v[132:135], v[210:213], v[28:31]
	v_mfma_f32_16x16x32_bf16 v[24:27], v[140:143], v[210:213], v[24:27]
	v_mfma_f32_16x16x32_bf16 v[12:15], v[132:135], v[218:221], v[12:15]
	v_mfma_f32_16x16x32_bf16 v[8:11], v[140:143], v[218:221], v[8:11]
	v_mfma_f32_16x16x32_bf16 v[52:55], v[144:147], v[190:193], v[52:55]
	v_mfma_f32_16x16x32_bf16 v[48:51], v[152:155], v[190:193], v[48:51]
	v_mfma_f32_16x16x32_bf16 v[36:39], v[144:147], v[198:201], v[36:39]
	v_mfma_f32_16x16x32_bf16 v[32:35], v[152:155], v[198:201], v[32:35]
	v_mfma_f32_16x16x32_bf16 v[20:23], v[144:147], v[206:209], v[20:23]
	v_mfma_f32_16x16x32_bf16 v[16:19], v[152:155], v[206:209], v[16:19]
	v_mfma_f32_16x16x32_bf16 v[4:7], v[144:147], v[214:217], v[4:7]
	v_mfma_f32_16x16x32_bf16 v[0:3], v[152:155], v[214:217], v[0:3]
	v_mfma_f32_16x16x32_bf16 v[52:55], v[148:151], v[194:197], v[52:55]
	v_mfma_f32_16x16x32_bf16 v[48:51], v[156:159], v[194:197], v[48:51]
	v_mfma_f32_16x16x32_bf16 v[36:39], v[148:151], v[202:205], v[36:39]
	v_mfma_f32_16x16x32_bf16 v[32:35], v[156:159], v[202:205], v[32:35]
	v_mfma_f32_16x16x32_bf16 v[20:23], v[148:151], v[210:213], v[20:23]
	v_mfma_f32_16x16x32_bf16 v[16:19], v[156:159], v[210:213], v[16:19]
	v_mfma_f32_16x16x32_bf16 v[4:7], v[148:151], v[218:221], v[4:7]
	v_mfma_f32_16x16x32_bf16 v[0:3], v[156:159], v[218:221], v[0:3]
	s_setprio 0
	s_barrier
	s_add_i32 s54, s54, 2
	s_cmp_gt_u32 s54, 13
	s_cbranch_scc1 .LBB0_66
	s_mov_b64 s[0:1], s[4:5]
	s_branch .LBB0_61
.LBB0_61:
	ds_read_b128 v[144:147], v178
	ds_read_b128 v[148:151], v178 offset:1024
	ds_read_b128 v[152:155], v178 offset:2048
	ds_read_b128 v[156:159], v178 offset:3072
	ds_read_b128 v[128:131], v179
	ds_read_b128 v[132:135], v179 offset:1024
	ds_read_b128 v[136:139], v179 offset:2048
	ds_read_b128 v[140:143], v179 offset:3072
	s_cmp_eq_u32 s54, 12
	s_cselect_b64 s[6:7], -1, 0
	s_add_u32 s4, s47, s0
	s_addc_u32 s5, s48, s1
	s_mov_b32 m0, s49
	ds_read_b128 v[190:193], v180
	ds_read_b128 v[194:197], v180 offset:1024
	ds_read_b128 v[198:201], v180 offset:2048
	ds_read_b128 v[202:205], v180 offset:3072
	ds_read_b128 v[206:209], v180 offset:4096
	ds_read_b128 v[210:213], v180 offset:5120
	ds_read_b128 v[214:217], v180 offset:6144
	ds_read_b128 v[218:221], v180 offset:7168
	global_load_lds_dwordx4 v168, s[4:5]
	s_mov_b32 m0, s50
	s_nop 0
	global_load_lds_dwordx4 v170, s[4:5]
	s_waitcnt vmcnt(8)
	s_waitcnt lgkmcnt(0)
	s_barrier
	s_setprio 1
	s_waitcnt lgkmcnt(0)
	v_mfma_f32_16x16x32_bf16 v[124:127], v[144:147], v[190:193], v[124:127]
	v_mfma_f32_16x16x32_bf16 v[120:123], v[152:155], v[190:193], v[120:123]
	v_mfma_f32_16x16x32_bf16 v[108:111], v[144:147], v[198:201], v[108:111]
	v_mfma_f32_16x16x32_bf16 v[104:107], v[152:155], v[198:201], v[104:107]
	v_mfma_f32_16x16x32_bf16 v[92:95], v[144:147], v[206:209], v[92:95]
	v_mfma_f32_16x16x32_bf16 v[88:91], v[152:155], v[206:209], v[88:91]
	v_mfma_f32_16x16x32_bf16 v[76:79], v[144:147], v[214:217], v[76:79]
	v_mfma_f32_16x16x32_bf16 v[72:75], v[152:155], v[214:217], v[72:75]
	v_mfma_f32_16x16x32_bf16 v[124:127], v[148:151], v[194:197], v[124:127]
	v_mfma_f32_16x16x32_bf16 v[120:123], v[156:159], v[194:197], v[120:123]
	v_mfma_f32_16x16x32_bf16 v[108:111], v[148:151], v[202:205], v[108:111]
	v_mfma_f32_16x16x32_bf16 v[104:107], v[156:159], v[202:205], v[104:107]
	v_mfma_f32_16x16x32_bf16 v[92:95], v[148:151], v[210:213], v[92:95]
	v_mfma_f32_16x16x32_bf16 v[88:91], v[156:159], v[210:213], v[88:91]
	v_mfma_f32_16x16x32_bf16 v[76:79], v[148:151], v[218:221], v[76:79]
	v_mfma_f32_16x16x32_bf16 v[72:75], v[156:159], v[218:221], v[72:75]
	v_mfma_f32_16x16x32_bf16 v[116:119], v[128:131], v[190:193], v[116:119]
	v_mfma_f32_16x16x32_bf16 v[112:115], v[136:139], v[190:193], v[112:115]
	v_mfma_f32_16x16x32_bf16 v[100:103], v[128:131], v[198:201], v[100:103]
	v_mfma_f32_16x16x32_bf16 v[96:99], v[136:139], v[198:201], v[96:99]
	v_mfma_f32_16x16x32_bf16 v[84:87], v[128:131], v[206:209], v[84:87]
	v_mfma_f32_16x16x32_bf16 v[80:83], v[136:139], v[206:209], v[80:83]
	v_mfma_f32_16x16x32_bf16 v[68:71], v[128:131], v[214:217], v[68:71]
	v_mfma_f32_16x16x32_bf16 v[64:67], v[136:139], v[214:217], v[64:67]
	v_mfma_f32_16x16x32_bf16 v[116:119], v[132:135], v[194:197], v[116:119]
	v_mfma_f32_16x16x32_bf16 v[112:115], v[140:143], v[194:197], v[112:115]
	v_mfma_f32_16x16x32_bf16 v[100:103], v[132:135], v[202:205], v[100:103]
	v_mfma_f32_16x16x32_bf16 v[96:99], v[140:143], v[202:205], v[96:99]
	v_mfma_f32_16x16x32_bf16 v[84:87], v[132:135], v[210:213], v[84:87]
	v_mfma_f32_16x16x32_bf16 v[80:83], v[140:143], v[210:213], v[80:83]
	v_mfma_f32_16x16x32_bf16 v[68:71], v[132:135], v[218:221], v[68:71]
	v_mfma_f32_16x16x32_bf16 v[64:67], v[140:143], v[218:221], v[64:67]
	s_setprio 0
	s_barrier
	s_and_b64 s[4:5], s[22:23], s[6:7]
	s_andn2_b64 vcc, exec, s[4:5]
	s_cbranch_vccnz .LBB0_63
	s_lshl_b32 s57, s29, 11
	s_lshl_b32 s58, s30, 11
	v_add_u32_e32 v164, s57, v247
	v_add_u32_e32 v168, s58, v247
	v_add_u32_e32 v166, 0x20000, v164
	v_add_u32_e32 v170, 0x20000, v168
	s_branch .LBB0_64
.LBB0_63:
.LBB0_64:
	s_add_u32 s4, s0, 0x100
	s_addc_u32 s5, s1, 0
	s_and_b64 s[56:57], s[6:7], exec
	s_cselect_b32 s8, 0, s4
	s_add_u32 s55, s31, s0
	s_addc_u32 s56, s53, s1
	s_and_b64 s[0:1], s[6:7], exec
	s_cselect_b32 s1, s21, s56
	s_cselect_b32 s0, s27, s55
	s_add_u32 s98, s2, s8
	s_addc_u32 s99, s3, s9
	s_mov_b32 m0, s35
	s_add_u32 s6, s0, 0x40000
	ds_read_b128 v[190:193], v180 offset:16384
	ds_read_b128 v[194:197], v180 offset:17408
	ds_read_b128 v[198:201], v180 offset:18432
	ds_read_b128 v[202:205], v180 offset:19456
	ds_read_b128 v[206:209], v180 offset:20480
	ds_read_b128 v[210:213], v180 offset:21504
	ds_read_b128 v[214:217], v180 offset:22528
	ds_read_b128 v[218:221], v180 offset:23552
	global_load_lds_dwordx4 v160, s[0:1]
	s_mov_b32 m0, s36
	s_addc_u32 s7, s1, 0
	global_load_lds_dwordx4 v162, s[0:1]
	s_mov_b32 m0, s37
	s_nop 0
	global_load_lds_dwordx4 v160, s[6:7]
	s_mov_b32 m0, s38
	s_nop 0
	global_load_lds_dwordx4 v162, s[6:7]
	s_mov_b32 m0, s34
	s_nop 0
	global_load_lds_dwordx4 v164, s[98:99]
	s_mov_b32 m0, s39
	s_nop 0
	global_load_lds_dwordx4 v166, s[98:99]
	s_waitcnt vmcnt(8)
	s_waitcnt lgkmcnt(0)
	s_barrier
	s_setprio 1
	s_waitcnt lgkmcnt(0)
	v_mfma_f32_16x16x32_bf16 v[60:63], v[144:147], v[190:193], v[60:63]
	v_mfma_f32_16x16x32_bf16 v[56:59], v[152:155], v[190:193], v[56:59]
	v_mfma_f32_16x16x32_bf16 v[44:47], v[144:147], v[198:201], v[44:47]
	v_mfma_f32_16x16x32_bf16 v[40:43], v[152:155], v[198:201], v[40:43]
	v_mfma_f32_16x16x32_bf16 v[28:31], v[144:147], v[206:209], v[28:31]
	v_mfma_f32_16x16x32_bf16 v[24:27], v[152:155], v[206:209], v[24:27]
	v_mfma_f32_16x16x32_bf16 v[12:15], v[144:147], v[214:217], v[12:15]
	v_mfma_f32_16x16x32_bf16 v[8:11], v[152:155], v[214:217], v[8:11]
	v_mfma_f32_16x16x32_bf16 v[60:63], v[148:151], v[194:197], v[60:63]
	v_mfma_f32_16x16x32_bf16 v[56:59], v[156:159], v[194:197], v[56:59]
	v_mfma_f32_16x16x32_bf16 v[44:47], v[148:151], v[202:205], v[44:47]
	v_mfma_f32_16x16x32_bf16 v[40:43], v[156:159], v[202:205], v[40:43]
	v_mfma_f32_16x16x32_bf16 v[28:31], v[148:151], v[210:213], v[28:31]
	v_mfma_f32_16x16x32_bf16 v[24:27], v[156:159], v[210:213], v[24:27]
	v_mfma_f32_16x16x32_bf16 v[12:15], v[148:151], v[218:221], v[12:15]
	v_mfma_f32_16x16x32_bf16 v[8:11], v[156:159], v[218:221], v[8:11]
	v_mfma_f32_16x16x32_bf16 v[52:55], v[128:131], v[190:193], v[52:55]
	v_mfma_f32_16x16x32_bf16 v[48:51], v[136:139], v[190:193], v[48:51]
	v_mfma_f32_16x16x32_bf16 v[36:39], v[128:131], v[198:201], v[36:39]
	v_mfma_f32_16x16x32_bf16 v[32:35], v[136:139], v[198:201], v[32:35]
	v_mfma_f32_16x16x32_bf16 v[20:23], v[128:131], v[206:209], v[20:23]
	v_mfma_f32_16x16x32_bf16 v[16:19], v[136:139], v[206:209], v[16:19]
	v_mfma_f32_16x16x32_bf16 v[4:7], v[128:131], v[214:217], v[4:7]
	v_mfma_f32_16x16x32_bf16 v[0:3], v[136:139], v[214:217], v[0:3]
	v_mfma_f32_16x16x32_bf16 v[52:55], v[132:135], v[194:197], v[52:55]
	v_mfma_f32_16x16x32_bf16 v[48:51], v[140:143], v[194:197], v[48:51]
	v_mfma_f32_16x16x32_bf16 v[36:39], v[132:135], v[202:205], v[36:39]
	v_mfma_f32_16x16x32_bf16 v[32:35], v[140:143], v[202:205], v[32:35]
	v_mfma_f32_16x16x32_bf16 v[20:23], v[132:135], v[210:213], v[20:23]
	v_mfma_f32_16x16x32_bf16 v[16:19], v[140:143], v[210:213], v[16:19]
	v_mfma_f32_16x16x32_bf16 v[4:7], v[132:135], v[218:221], v[4:7]
	v_mfma_f32_16x16x32_bf16 v[0:3], v[140:143], v[218:221], v[0:3]
	s_setprio 0
	s_barrier
	s_add_i32 s6, 0, 0x18000
	s_add_i32 s7, 0, 0x1c000
	v_add_u32_e32 v140, s6, v176
	v_add_u32_e32 v156, s7, v176
	ds_read_b128 v[128:131], v140
	ds_read_b128 v[132:135], v140 offset:1024
	ds_read_b128 v[136:139], v140 offset:2048
	ds_read_b128 v[140:143], v140 offset:3072
	ds_read_b128 v[144:147], v156
	ds_read_b128 v[148:151], v156 offset:1024
	ds_read_b128 v[152:155], v156 offset:2048
	ds_read_b128 v[156:159], v156 offset:3072
	s_mov_b32 m0, s40
	ds_read_b128 v[190:193], v180 offset:32768
	ds_read_b128 v[194:197], v180 offset:33792
	ds_read_b128 v[198:201], v180 offset:34816
	ds_read_b128 v[202:205], v180 offset:35840
	ds_read_b128 v[206:209], v180 offset:36864
	ds_read_b128 v[210:213], v180 offset:37888
	ds_read_b128 v[214:217], v180 offset:38912
	ds_read_b128 v[218:221], v180 offset:39936
	global_load_lds_dwordx4 v168, s[98:99]
	s_mov_b32 m0, s41
	s_nop 0
	global_load_lds_dwordx4 v170, s[98:99]
	s_waitcnt vmcnt(8)
	s_waitcnt lgkmcnt(0)
	s_barrier
	s_setprio 1
	s_waitcnt lgkmcnt(0)
	v_mfma_f32_16x16x32_bf16 v[124:127], v[128:131], v[190:193], v[124:127]
	v_mfma_f32_16x16x32_bf16 v[120:123], v[136:139], v[190:193], v[120:123]
	v_mfma_f32_16x16x32_bf16 v[108:111], v[128:131], v[198:201], v[108:111]
	v_mfma_f32_16x16x32_bf16 v[104:107], v[136:139], v[198:201], v[104:107]
	v_mfma_f32_16x16x32_bf16 v[92:95], v[128:131], v[206:209], v[92:95]
	v_mfma_f32_16x16x32_bf16 v[88:91], v[136:139], v[206:209], v[88:91]
	v_mfma_f32_16x16x32_bf16 v[76:79], v[128:131], v[214:217], v[76:79]
	v_mfma_f32_16x16x32_bf16 v[72:75], v[136:139], v[214:217], v[72:75]
	v_mfma_f32_16x16x32_bf16 v[124:127], v[132:135], v[194:197], v[124:127]
	v_mfma_f32_16x16x32_bf16 v[120:123], v[140:143], v[194:197], v[120:123]
	v_mfma_f32_16x16x32_bf16 v[108:111], v[132:135], v[202:205], v[108:111]
	v_mfma_f32_16x16x32_bf16 v[104:107], v[140:143], v[202:205], v[104:107]
	v_mfma_f32_16x16x32_bf16 v[92:95], v[132:135], v[210:213], v[92:95]
	v_mfma_f32_16x16x32_bf16 v[88:91], v[140:143], v[210:213], v[88:91]
	v_mfma_f32_16x16x32_bf16 v[76:79], v[132:135], v[218:221], v[76:79]
	v_mfma_f32_16x16x32_bf16 v[72:75], v[140:143], v[218:221], v[72:75]
	v_mfma_f32_16x16x32_bf16 v[116:119], v[144:147], v[190:193], v[116:119]
	v_mfma_f32_16x16x32_bf16 v[112:115], v[152:155], v[190:193], v[112:115]
	v_mfma_f32_16x16x32_bf16 v[100:103], v[144:147], v[198:201], v[100:103]
	v_mfma_f32_16x16x32_bf16 v[96:99], v[152:155], v[198:201], v[96:99]
	v_mfma_f32_16x16x32_bf16 v[84:87], v[144:147], v[206:209], v[84:87]
	v_mfma_f32_16x16x32_bf16 v[80:83], v[152:155], v[206:209], v[80:83]
	v_mfma_f32_16x16x32_bf16 v[68:71], v[144:147], v[214:217], v[68:71]
	v_mfma_f32_16x16x32_bf16 v[64:67], v[152:155], v[214:217], v[64:67]
	v_mfma_f32_16x16x32_bf16 v[116:119], v[148:151], v[194:197], v[116:119]
	v_mfma_f32_16x16x32_bf16 v[112:115], v[156:159], v[194:197], v[112:115]
	v_mfma_f32_16x16x32_bf16 v[100:103], v[148:151], v[202:205], v[100:103]
	v_mfma_f32_16x16x32_bf16 v[96:99], v[156:159], v[202:205], v[96:99]
	v_mfma_f32_16x16x32_bf16 v[84:87], v[148:151], v[210:213], v[84:87]
	v_mfma_f32_16x16x32_bf16 v[80:83], v[156:159], v[210:213], v[80:83]
	v_mfma_f32_16x16x32_bf16 v[68:71], v[148:151], v[218:221], v[68:71]
	v_mfma_f32_16x16x32_bf16 v[64:67], v[156:159], v[218:221], v[64:67]
	s_setprio 0
	s_barrier
	s_add_i32 s6, s6, s84
	s_add_u32 s100, s0, s14
	s_addc_u32 s101, s1, s15
	s_add_u32 s98, s98, s14
	s_addc_u32 s99, s99, s15
	s_mov_b32 m0, s6
	ds_read_b128 v[190:193], v180 offset:49152
	ds_read_b128 v[194:197], v180 offset:50176
	ds_read_b128 v[198:201], v180 offset:51200
	ds_read_b128 v[202:205], v180 offset:52224
	ds_read_b128 v[206:209], v180 offset:53248
	ds_read_b128 v[210:213], v180 offset:54272
	ds_read_b128 v[214:217], v180 offset:55296
	ds_read_b128 v[218:221], v180 offset:56320
	global_load_lds_dwordx4 v160, s[100:101]
	s_add_i32 m0, s6, 0x2000
	s_add_u32 s0, s0, 0x40080
	s_addc_u32 s1, s1, 0
	s_add_i32 s6, s7, s84
	global_load_lds_dwordx4 v162, s[100:101]
	s_mov_b32 m0, s6
	s_nop 0
	global_load_lds_dwordx4 v160, s[0:1]
	s_add_i32 m0, s6, 0x2000
	s_nop 0
	global_load_lds_dwordx4 v162, s[0:1]
	s_mov_b32 m0, s42
	s_nop 0
	global_load_lds_dwordx4 v164, s[98:99]
	s_mov_b32 m0, s43
	s_nop 0
	global_load_lds_dwordx4 v166, s[98:99]
	s_waitcnt vmcnt(8)
	s_waitcnt lgkmcnt(0)
	s_barrier
	s_setprio 1
	s_waitcnt lgkmcnt(0)
	v_mfma_f32_16x16x32_bf16 v[60:63], v[128:131], v[190:193], v[60:63]
	v_mfma_f32_16x16x32_bf16 v[56:59], v[136:139], v[190:193], v[56:59]
	v_mfma_f32_16x16x32_bf16 v[44:47], v[128:131], v[198:201], v[44:47]
	v_mfma_f32_16x16x32_bf16 v[40:43], v[136:139], v[198:201], v[40:43]
	v_mfma_f32_16x16x32_bf16 v[28:31], v[128:131], v[206:209], v[28:31]
	v_mfma_f32_16x16x32_bf16 v[24:27], v[136:139], v[206:209], v[24:27]
	v_mfma_f32_16x16x32_bf16 v[12:15], v[128:131], v[214:217], v[12:15]
	v_mfma_f32_16x16x32_bf16 v[8:11], v[136:139], v[214:217], v[8:11]
	v_mfma_f32_16x16x32_bf16 v[60:63], v[132:135], v[194:197], v[60:63]
	v_mfma_f32_16x16x32_bf16 v[56:59], v[140:143], v[194:197], v[56:59]
	v_mfma_f32_16x16x32_bf16 v[44:47], v[132:135], v[202:205], v[44:47]
	v_mfma_f32_16x16x32_bf16 v[40:43], v[140:143], v[202:205], v[40:43]
	v_mfma_f32_16x16x32_bf16 v[28:31], v[132:135], v[210:213], v[28:31]
	v_mfma_f32_16x16x32_bf16 v[24:27], v[140:143], v[210:213], v[24:27]
	v_mfma_f32_16x16x32_bf16 v[12:15], v[132:135], v[218:221], v[12:15]
	v_mfma_f32_16x16x32_bf16 v[8:11], v[140:143], v[218:221], v[8:11]
	v_mfma_f32_16x16x32_bf16 v[52:55], v[144:147], v[190:193], v[52:55]
	v_mfma_f32_16x16x32_bf16 v[48:51], v[152:155], v[190:193], v[48:51]
	v_mfma_f32_16x16x32_bf16 v[36:39], v[144:147], v[198:201], v[36:39]
	v_mfma_f32_16x16x32_bf16 v[32:35], v[152:155], v[198:201], v[32:35]
	v_mfma_f32_16x16x32_bf16 v[20:23], v[144:147], v[206:209], v[20:23]
	v_mfma_f32_16x16x32_bf16 v[16:19], v[152:155], v[206:209], v[16:19]
	v_mfma_f32_16x16x32_bf16 v[4:7], v[144:147], v[214:217], v[4:7]
	v_mfma_f32_16x16x32_bf16 v[0:3], v[152:155], v[214:217], v[0:3]
	v_mfma_f32_16x16x32_bf16 v[52:55], v[148:151], v[194:197], v[52:55]
	v_mfma_f32_16x16x32_bf16 v[48:51], v[156:159], v[194:197], v[48:51]
	v_mfma_f32_16x16x32_bf16 v[36:39], v[148:151], v[202:205], v[36:39]
	v_mfma_f32_16x16x32_bf16 v[32:35], v[156:159], v[202:205], v[32:35]
	v_mfma_f32_16x16x32_bf16 v[20:23], v[148:151], v[210:213], v[20:23]
	v_mfma_f32_16x16x32_bf16 v[16:19], v[156:159], v[210:213], v[16:19]
	v_mfma_f32_16x16x32_bf16 v[4:7], v[148:151], v[218:221], v[4:7]
	v_mfma_f32_16x16x32_bf16 v[0:3], v[156:159], v[218:221], v[0:3]
	s_setprio 0
	s_barrier
	s_add_i32 s54, s54, 2
	s_cmp_gt_u32 s54, 13
	s_cbranch_scc1 .LBB0_66
	s_mov_b64 s[0:1], s[4:5]
	s_branch .LBB0_61

.LBB0_720:
	s_ashr_i32 s15, s14, 31
	s_lshl_b64 s[18:19], s[14:15], 19
	s_add_u32 s18, s13, s18
	s_addc_u32 s19, s26, s19
	s_and_b64 s[22:23], s[16:17], exec
	s_cselect_b32 s15, s19, s21
	s_cselect_b32 s46, s18, s20
	s_lshl_b32 s47, s43, 8
	s_or_b32 s48, s47, 0x80
	s_add_u32 s49, s20, 0x100
	s_addc_u32 s50, s21, 0
	s_mov_b32 s51, -2
	s_mov_b64 s[20:21], 0
	s_waitcnt vmcnt(0)
	ds_read_b128 v[144:147], v177
	ds_read_b128 v[148:151], v177 offset:1024
	ds_read_b128 v[152:155], v177 offset:2048
	ds_read_b128 v[156:159], v177 offset:3072
	ds_read_b128 v[128:131], v178
	ds_read_b128 v[132:135], v178 offset:1024
	ds_read_b128 v[136:139], v178 offset:2048
	ds_read_b128 v[140:143], v178 offset:3072
	s_cmp_eq_u32 s51, 12
	s_cselect_b64 s[24:25], -1, 0
	s_add_i32 m0, s27, 0xc000
	s_add_u32 s22, s40, s20
	s_addc_u32 s23, s41, s21
	ds_read_b128 v[180:183], v179
	ds_read_b128 v[184:187], v179 offset:1024
	ds_read_b128 v[188:191], v179 offset:2048
	ds_read_b128 v[192:195], v179 offset:3072
	ds_read_b128 v[196:199], v179 offset:4096
	ds_read_b128 v[200:203], v179 offset:5120
	ds_read_b128 v[204:207], v179 offset:6144
	ds_read_b128 v[208:211], v179 offset:7168
	global_load_lds_dwordx4 v168, s[22:23]
	s_add_i32 m0, s27, 0xe000
	s_nop 0
	global_load_lds_dwordx4 v170, s[22:23]
	s_waitcnt vmcnt(8)
	s_waitcnt lgkmcnt(0)
	s_barrier
	s_setprio 1
	s_waitcnt lgkmcnt(0)
	v_mfma_f32_16x16x32_bf16 v[124:127], v[144:147], v[180:183], 0
	v_mfma_f32_16x16x32_bf16 v[120:123], v[152:155], v[180:183], 0
	v_mfma_f32_16x16x32_bf16 v[112:115], v[144:147], v[188:191], 0
	v_mfma_f32_16x16x32_bf16 v[104:107], v[152:155], v[188:191], 0
	v_mfma_f32_16x16x32_bf16 v[96:99], v[144:147], v[196:199], 0
	v_mfma_f32_16x16x32_bf16 v[88:91], v[152:155], v[196:199], 0
	v_mfma_f32_16x16x32_bf16 v[80:83], v[144:147], v[204:207], 0
	v_mfma_f32_16x16x32_bf16 v[72:75], v[152:155], v[204:207], 0
	v_mfma_f32_16x16x32_bf16 v[124:127], v[148:151], v[184:187], v[124:127]
	v_mfma_f32_16x16x32_bf16 v[120:123], v[156:159], v[184:187], v[120:123]
	v_mfma_f32_16x16x32_bf16 v[112:115], v[148:151], v[192:195], v[112:115]
	v_mfma_f32_16x16x32_bf16 v[104:107], v[156:159], v[192:195], v[104:107]
	v_mfma_f32_16x16x32_bf16 v[96:99], v[148:151], v[200:203], v[96:99]
	v_mfma_f32_16x16x32_bf16 v[88:91], v[156:159], v[200:203], v[88:91]
	v_mfma_f32_16x16x32_bf16 v[80:83], v[148:151], v[208:211], v[80:83]
	v_mfma_f32_16x16x32_bf16 v[72:75], v[156:159], v[208:211], v[72:75]
	v_mfma_f32_16x16x32_bf16 v[116:119], v[128:131], v[180:183], 0
	v_mfma_f32_16x16x32_bf16 v[108:111], v[136:139], v[180:183], 0
	v_mfma_f32_16x16x32_bf16 v[100:103], v[128:131], v[188:191], 0
	v_mfma_f32_16x16x32_bf16 v[92:95], v[136:139], v[188:191], 0
	v_mfma_f32_16x16x32_bf16 v[84:87], v[128:131], v[196:199], 0
	v_mfma_f32_16x16x32_bf16 v[76:79], v[136:139], v[196:199], 0
	v_mfma_f32_16x16x32_bf16 v[68:71], v[128:131], v[204:207], 0
	v_mfma_f32_16x16x32_bf16 v[64:67], v[136:139], v[204:207], 0
	v_mfma_f32_16x16x32_bf16 v[116:119], v[132:135], v[184:187], v[116:119]
	v_mfma_f32_16x16x32_bf16 v[108:111], v[140:143], v[184:187], v[108:111]
	v_mfma_f32_16x16x32_bf16 v[100:103], v[132:135], v[192:195], v[100:103]
	v_mfma_f32_16x16x32_bf16 v[92:95], v[140:143], v[192:195], v[92:95]
	v_mfma_f32_16x16x32_bf16 v[84:87], v[132:135], v[200:203], v[84:87]
	v_mfma_f32_16x16x32_bf16 v[76:79], v[140:143], v[200:203], v[76:79]
	v_mfma_f32_16x16x32_bf16 v[68:71], v[132:135], v[208:211], v[68:71]
	v_mfma_f32_16x16x32_bf16 v[64:67], v[140:143], v[208:211], v[64:67]
	s_setprio 0
	s_barrier
	s_and_b64 s[22:23], s[16:17], s[24:25]
	s_andn2_b64 vcc, exec, s[22:23]
	s_cbranch_vccnz .Lpk1_LBB0_723
	s_lshl_b32 s57, s47, 11
	s_lshl_b32 s58, s48, 11
	v_add_u32_e32 v164, s57, v247
	v_add_u32_e32 v168, s58, v247
	v_add_u32_e32 v166, 0x20000, v164
	v_add_u32_e32 v170, 0x20000, v168
	s_branch .Lpk1_LBB0_724
.Lpk1_LBB0_723:
.Lpk1_LBB0_724:
	s_add_u32 s22, s20, 0x100
	s_addc_u32 s23, s21, 0
	s_and_b64 s[52:53], s[24:25], exec
	s_cselect_b32 s0, 0, s22
	s_add_u32 s52, s49, s20
	s_addc_u32 s53, s50, s21
	s_and_b64 s[20:21], s[24:25], exec
	s_cselect_b32 s21, s15, s53
	s_cselect_b32 s20, s46, s52
	s_add_u32 s98, s2, s0
	s_addc_u32 s99, s3, s1
	s_mov_b32 m0, s28
	s_add_u32 s24, s20, 0x40000
	ds_read_b128 v[180:183], v179 offset:16384
	ds_read_b128 v[184:187], v179 offset:17408
	ds_read_b128 v[188:191], v179 offset:18432
	ds_read_b128 v[192:195], v179 offset:19456
	ds_read_b128 v[196:199], v179 offset:20480
	ds_read_b128 v[200:203], v179 offset:21504
	ds_read_b128 v[204:207], v179 offset:22528
	ds_read_b128 v[208:211], v179 offset:23552
	global_load_lds_dwordx4 v162, s[20:21]
	s_mov_b32 m0, s29
	s_addc_u32 s25, s21, 0
	global_load_lds_dwordx4 v160, s[20:21]
	s_mov_b32 m0, s30
	s_nop 0
	global_load_lds_dwordx4 v162, s[24:25]
	s_mov_b32 m0, s31
	s_nop 0
	global_load_lds_dwordx4 v160, s[24:25]
	s_mov_b32 m0, s27
	s_nop 0
	global_load_lds_dwordx4 v164, s[98:99]
	s_mov_b32 m0, s34
	s_nop 0
	global_load_lds_dwordx4 v166, s[98:99]
	s_waitcnt vmcnt(8)
	s_waitcnt lgkmcnt(0)
	s_barrier
	s_setprio 1
	s_waitcnt lgkmcnt(0)
	v_mfma_f32_16x16x32_bf16 v[60:63], v[144:147], v[180:183], 0
	v_mfma_f32_16x16x32_bf16 v[56:59], v[152:155], v[180:183], 0
	v_mfma_f32_16x16x32_bf16 v[48:51], v[144:147], v[188:191], 0
	v_mfma_f32_16x16x32_bf16 v[40:43], v[152:155], v[188:191], 0
	v_mfma_f32_16x16x32_bf16 v[32:35], v[144:147], v[196:199], 0
	v_mfma_f32_16x16x32_bf16 v[24:27], v[152:155], v[196:199], 0
	v_mfma_f32_16x16x32_bf16 v[16:19], v[144:147], v[204:207], 0
	v_mfma_f32_16x16x32_bf16 v[8:11], v[152:155], v[204:207], 0
	v_mfma_f32_16x16x32_bf16 v[60:63], v[148:151], v[184:187], v[60:63]
	v_mfma_f32_16x16x32_bf16 v[56:59], v[156:159], v[184:187], v[56:59]
	v_mfma_f32_16x16x32_bf16 v[48:51], v[148:151], v[192:195], v[48:51]
	v_mfma_f32_16x16x32_bf16 v[40:43], v[156:159], v[192:195], v[40:43]
	v_mfma_f32_16x16x32_bf16 v[32:35], v[148:151], v[200:203], v[32:35]
	v_mfma_f32_16x16x32_bf16 v[24:27], v[156:159], v[200:203], v[24:27]
	v_mfma_f32_16x16x32_bf16 v[16:19], v[148:151], v[208:211], v[16:19]
	v_mfma_f32_16x16x32_bf16 v[8:11], v[156:159], v[208:211], v[8:11]
	v_mfma_f32_16x16x32_bf16 v[52:55], v[128:131], v[180:183], 0
	v_mfma_f32_16x16x32_bf16 v[44:47], v[136:139], v[180:183], 0
	v_mfma_f32_16x16x32_bf16 v[36:39], v[128:131], v[188:191], 0
	v_mfma_f32_16x16x32_bf16 v[28:31], v[136:139], v[188:191], 0
	v_mfma_f32_16x16x32_bf16 v[20:23], v[128:131], v[196:199], 0
	v_mfma_f32_16x16x32_bf16 v[12:15], v[136:139], v[196:199], 0
	v_mfma_f32_16x16x32_bf16 v[4:7], v[128:131], v[204:207], 0
	v_mfma_f32_16x16x32_bf16 v[0:3], v[136:139], v[204:207], 0
	v_mfma_f32_16x16x32_bf16 v[52:55], v[132:135], v[184:187], v[52:55]
	v_mfma_f32_16x16x32_bf16 v[44:47], v[140:143], v[184:187], v[44:47]
	v_mfma_f32_16x16x32_bf16 v[36:39], v[132:135], v[192:195], v[36:39]
	v_mfma_f32_16x16x32_bf16 v[28:31], v[140:143], v[192:195], v[28:31]
	v_mfma_f32_16x16x32_bf16 v[20:23], v[132:135], v[200:203], v[20:23]
	v_mfma_f32_16x16x32_bf16 v[12:15], v[140:143], v[200:203], v[12:15]
	v_mfma_f32_16x16x32_bf16 v[4:7], v[132:135], v[208:211], v[4:7]
	v_mfma_f32_16x16x32_bf16 v[0:3], v[140:143], v[208:211], v[0:3]
	s_setprio 0
	s_barrier
	s_add_i32 s24, 0, 0x18000
	s_add_i32 s25, 0, 0x1c000
	v_add_u32_e32 v140, s24, v176
	v_add_u32_e32 v156, s25, v176
	ds_read_b128 v[128:131], v140
	ds_read_b128 v[132:135], v140 offset:1024
	ds_read_b128 v[136:139], v140 offset:2048
	ds_read_b128 v[140:143], v140 offset:3072
	ds_read_b128 v[144:147], v156
	ds_read_b128 v[148:151], v156 offset:1024
	ds_read_b128 v[152:155], v156 offset:2048
	ds_read_b128 v[156:159], v156 offset:3072
	s_mov_b32 m0, s35
	ds_read_b128 v[180:183], v179 offset:32768
	ds_read_b128 v[184:187], v179 offset:33792
	ds_read_b128 v[188:191], v179 offset:34816
	ds_read_b128 v[192:195], v179 offset:35840
	ds_read_b128 v[196:199], v179 offset:36864
	ds_read_b128 v[200:203], v179 offset:37888
	ds_read_b128 v[204:207], v179 offset:38912
	ds_read_b128 v[208:211], v179 offset:39936
	global_load_lds_dwordx4 v168, s[98:99]
	s_mov_b32 m0, s36
	s_nop 0
	global_load_lds_dwordx4 v170, s[98:99]
	s_waitcnt vmcnt(8)
	s_waitcnt lgkmcnt(0)
	s_barrier
	s_setprio 1
	s_waitcnt lgkmcnt(0)
	v_mfma_f32_16x16x32_bf16 v[124:127], v[128:131], v[180:183], v[124:127]
	v_mfma_f32_16x16x32_bf16 v[120:123], v[136:139], v[180:183], v[120:123]
	v_mfma_f32_16x16x32_bf16 v[112:115], v[128:131], v[188:191], v[112:115]
	v_mfma_f32_16x16x32_bf16 v[104:107], v[136:139], v[188:191], v[104:107]
	v_mfma_f32_16x16x32_bf16 v[96:99], v[128:131], v[196:199], v[96:99]
	v_mfma_f32_16x16x32_bf16 v[88:91], v[136:139], v[196:199], v[88:91]
	v_mfma_f32_16x16x32_bf16 v[80:83], v[128:131], v[204:207], v[80:83]
	v_mfma_f32_16x16x32_bf16 v[72:75], v[136:139], v[204:207], v[72:75]
	v_mfma_f32_16x16x32_bf16 v[124:127], v[132:135], v[184:187], v[124:127]
	v_mfma_f32_16x16x32_bf16 v[120:123], v[140:143], v[184:187], v[120:123]
	v_mfma_f32_16x16x32_bf16 v[112:115], v[132:135], v[192:195], v[112:115]
	v_mfma_f32_16x16x32_bf16 v[104:107], v[140:143], v[192:195], v[104:107]
	v_mfma_f32_16x16x32_bf16 v[96:99], v[132:135], v[200:203], v[96:99]
	v_mfma_f32_16x16x32_bf16 v[88:91], v[140:143], v[200:203], v[88:91]
	v_mfma_f32_16x16x32_bf16 v[80:83], v[132:135], v[208:211], v[80:83]
	v_mfma_f32_16x16x32_bf16 v[72:75], v[140:143], v[208:211], v[72:75]
	v_mfma_f32_16x16x32_bf16 v[116:119], v[144:147], v[180:183], v[116:119]
	v_mfma_f32_16x16x32_bf16 v[108:111], v[152:155], v[180:183], v[108:111]
	v_mfma_f32_16x16x32_bf16 v[100:103], v[144:147], v[188:191], v[100:103]
	v_mfma_f32_16x16x32_bf16 v[92:95], v[152:155], v[188:191], v[92:95]
	v_mfma_f32_16x16x32_bf16 v[84:87], v[144:147], v[196:199], v[84:87]
	v_mfma_f32_16x16x32_bf16 v[76:79], v[152:155], v[196:199], v[76:79]
	v_mfma_f32_16x16x32_bf16 v[68:71], v[144:147], v[204:207], v[68:71]
	v_mfma_f32_16x16x32_bf16 v[64:67], v[152:155], v[204:207], v[64:67]
	v_mfma_f32_16x16x32_bf16 v[116:119], v[148:151], v[184:187], v[116:119]
	v_mfma_f32_16x16x32_bf16 v[108:111], v[156:159], v[184:187], v[108:111]
	v_mfma_f32_16x16x32_bf16 v[100:103], v[148:151], v[192:195], v[100:103]
	v_mfma_f32_16x16x32_bf16 v[92:95], v[156:159], v[192:195], v[92:95]
	v_mfma_f32_16x16x32_bf16 v[84:87], v[148:151], v[200:203], v[84:87]
	v_mfma_f32_16x16x32_bf16 v[76:79], v[156:159], v[200:203], v[76:79]
	v_mfma_f32_16x16x32_bf16 v[68:71], v[148:151], v[208:211], v[68:71]
	v_mfma_f32_16x16x32_bf16 v[64:67], v[156:159], v[208:211], v[64:67]
	s_setprio 0
	s_barrier
	s_add_i32 s0, s24, s84
	s_add_u32 s100, s20, s6
	s_addc_u32 s101, s21, s7
	s_add_u32 s98, s98, s6
	s_addc_u32 s99, s99, s7
	s_mov_b32 m0, s0
	ds_read_b128 v[180:183], v179 offset:49152
	ds_read_b128 v[184:187], v179 offset:50176
	ds_read_b128 v[188:191], v179 offset:51200
	ds_read_b128 v[192:195], v179 offset:52224
	ds_read_b128 v[196:199], v179 offset:53248
	ds_read_b128 v[200:203], v179 offset:54272
	ds_read_b128 v[204:207], v179 offset:55296
	ds_read_b128 v[208:211], v179 offset:56320
	global_load_lds_dwordx4 v162, s[100:101]
	s_add_i32 m0, s0, 0x2000
	s_add_u32 s20, s20, 0x40080
	s_addc_u32 s21, s21, 0
	s_add_i32 s0, s25, s84
	global_load_lds_dwordx4 v160, s[100:101]
	s_mov_b32 m0, s0
	s_nop 0
	global_load_lds_dwordx4 v162, s[20:21]
	s_add_i32 m0, s0, 0x2000
	s_nop 0
	global_load_lds_dwordx4 v160, s[20:21]
	s_mov_b32 m0, s37
	s_nop 0
	global_load_lds_dwordx4 v164, s[98:99]
	s_mov_b32 m0, s38
	s_nop 0
	global_load_lds_dwordx4 v166, s[98:99]
	s_waitcnt vmcnt(8)
	s_waitcnt lgkmcnt(0)
	s_barrier
	s_setprio 1
	s_waitcnt lgkmcnt(0)
	v_mfma_f32_16x16x32_bf16 v[60:63], v[128:131], v[180:183], v[60:63]
	v_mfma_f32_16x16x32_bf16 v[56:59], v[136:139], v[180:183], v[56:59]
	v_mfma_f32_16x16x32_bf16 v[48:51], v[128:131], v[188:191], v[48:51]
	v_mfma_f32_16x16x32_bf16 v[40:43], v[136:139], v[188:191], v[40:43]
	v_mfma_f32_16x16x32_bf16 v[32:35], v[128:131], v[196:199], v[32:35]
	v_mfma_f32_16x16x32_bf16 v[24:27], v[136:139], v[196:199], v[24:27]
	v_mfma_f32_16x16x32_bf16 v[16:19], v[128:131], v[204:207], v[16:19]
	v_mfma_f32_16x16x32_bf16 v[8:11], v[136:139], v[204:207], v[8:11]
	v_mfma_f32_16x16x32_bf16 v[60:63], v[132:135], v[184:187], v[60:63]
	v_mfma_f32_16x16x32_bf16 v[56:59], v[140:143], v[184:187], v[56:59]
	v_mfma_f32_16x16x32_bf16 v[48:51], v[132:135], v[192:195], v[48:51]
	v_mfma_f32_16x16x32_bf16 v[40:43], v[140:143], v[192:195], v[40:43]
	v_mfma_f32_16x16x32_bf16 v[32:35], v[132:135], v[200:203], v[32:35]
	v_mfma_f32_16x16x32_bf16 v[24:27], v[140:143], v[200:203], v[24:27]
	v_mfma_f32_16x16x32_bf16 v[16:19], v[132:135], v[208:211], v[16:19]
	v_mfma_f32_16x16x32_bf16 v[8:11], v[140:143], v[208:211], v[8:11]
	v_mfma_f32_16x16x32_bf16 v[52:55], v[144:147], v[180:183], v[52:55]
	v_mfma_f32_16x16x32_bf16 v[44:47], v[152:155], v[180:183], v[44:47]
	v_mfma_f32_16x16x32_bf16 v[36:39], v[144:147], v[188:191], v[36:39]
	v_mfma_f32_16x16x32_bf16 v[28:31], v[152:155], v[188:191], v[28:31]
	v_mfma_f32_16x16x32_bf16 v[20:23], v[144:147], v[196:199], v[20:23]
	v_mfma_f32_16x16x32_bf16 v[12:15], v[152:155], v[196:199], v[12:15]
	v_mfma_f32_16x16x32_bf16 v[4:7], v[144:147], v[204:207], v[4:7]
	v_mfma_f32_16x16x32_bf16 v[0:3], v[152:155], v[204:207], v[0:3]
	v_mfma_f32_16x16x32_bf16 v[52:55], v[148:151], v[184:187], v[52:55]
	v_mfma_f32_16x16x32_bf16 v[44:47], v[156:159], v[184:187], v[44:47]
	v_mfma_f32_16x16x32_bf16 v[36:39], v[148:151], v[192:195], v[36:39]
	v_mfma_f32_16x16x32_bf16 v[28:31], v[156:159], v[192:195], v[28:31]
	v_mfma_f32_16x16x32_bf16 v[20:23], v[148:151], v[200:203], v[20:23]
	v_mfma_f32_16x16x32_bf16 v[12:15], v[156:159], v[200:203], v[12:15]
	v_mfma_f32_16x16x32_bf16 v[4:7], v[148:151], v[208:211], v[4:7]
	v_mfma_f32_16x16x32_bf16 v[0:3], v[156:159], v[208:211], v[0:3]
	s_setprio 0
	s_barrier
	s_add_i32 s51, s51, 2
	s_cmp_gt_u32 s51, 13
	s_cbranch_scc1 .LBB0_726
	s_mov_b64 s[20:21], s[22:23]
	s_branch .LBB0_721
.LBB0_721:
	ds_read_b128 v[144:147], v177
	ds_read_b128 v[148:151], v177 offset:1024
	ds_read_b128 v[152:155], v177 offset:2048
	ds_read_b128 v[156:159], v177 offset:3072
	ds_read_b128 v[128:131], v178
	ds_read_b128 v[132:135], v178 offset:1024
	ds_read_b128 v[136:139], v178 offset:2048
	ds_read_b128 v[140:143], v178 offset:3072
	s_cmp_eq_u32 s51, 12
	s_cselect_b64 s[24:25], -1, 0
	s_add_i32 m0, s27, 0xc000
	s_add_u32 s22, s40, s20
	s_addc_u32 s23, s41, s21
	ds_read_b128 v[180:183], v179
	ds_read_b128 v[184:187], v179 offset:1024
	ds_read_b128 v[188:191], v179 offset:2048
	ds_read_b128 v[192:195], v179 offset:3072
	ds_read_b128 v[196:199], v179 offset:4096
	ds_read_b128 v[200:203], v179 offset:5120
	ds_read_b128 v[204:207], v179 offset:6144
	ds_read_b128 v[208:211], v179 offset:7168
	global_load_lds_dwordx4 v168, s[22:23]
	s_add_i32 m0, s27, 0xe000
	s_nop 0
	global_load_lds_dwordx4 v170, s[22:23]
	s_waitcnt vmcnt(8)
	s_waitcnt lgkmcnt(0)
	s_barrier
	s_setprio 1
	s_waitcnt lgkmcnt(0)
	v_mfma_f32_16x16x32_bf16 v[124:127], v[144:147], v[180:183], v[124:127]
	v_mfma_f32_16x16x32_bf16 v[120:123], v[152:155], v[180:183], v[120:123]
	v_mfma_f32_16x16x32_bf16 v[112:115], v[144:147], v[188:191], v[112:115]
	v_mfma_f32_16x16x32_bf16 v[104:107], v[152:155], v[188:191], v[104:107]
	v_mfma_f32_16x16x32_bf16 v[96:99], v[144:147], v[196:199], v[96:99]
	v_mfma_f32_16x16x32_bf16 v[88:91], v[152:155], v[196:199], v[88:91]
	v_mfma_f32_16x16x32_bf16 v[80:83], v[144:147], v[204:207], v[80:83]
	v_mfma_f32_16x16x32_bf16 v[72:75], v[152:155], v[204:207], v[72:75]
	v_mfma_f32_16x16x32_bf16 v[124:127], v[148:151], v[184:187], v[124:127]
	v_mfma_f32_16x16x32_bf16 v[120:123], v[156:159], v[184:187], v[120:123]
	v_mfma_f32_16x16x32_bf16 v[112:115], v[148:151], v[192:195], v[112:115]
	v_mfma_f32_16x16x32_bf16 v[104:107], v[156:159], v[192:195], v[104:107]
	v_mfma_f32_16x16x32_bf16 v[96:99], v[148:151], v[200:203], v[96:99]
	v_mfma_f32_16x16x32_bf16 v[88:91], v[156:159], v[200:203], v[88:91]
	v_mfma_f32_16x16x32_bf16 v[80:83], v[148:151], v[208:211], v[80:83]
	v_mfma_f32_16x16x32_bf16 v[72:75], v[156:159], v[208:211], v[72:75]
	v_mfma_f32_16x16x32_bf16 v[116:119], v[128:131], v[180:183], v[116:119]
	v_mfma_f32_16x16x32_bf16 v[108:111], v[136:139], v[180:183], v[108:111]
	v_mfma_f32_16x16x32_bf16 v[100:103], v[128:131], v[188:191], v[100:103]
	v_mfma_f32_16x16x32_bf16 v[92:95], v[136:139], v[188:191], v[92:95]
	v_mfma_f32_16x16x32_bf16 v[84:87], v[128:131], v[196:199], v[84:87]
	v_mfma_f32_16x16x32_bf16 v[76:79], v[136:139], v[196:199], v[76:79]
	v_mfma_f32_16x16x32_bf16 v[68:71], v[128:131], v[204:207], v[68:71]
	v_mfma_f32_16x16x32_bf16 v[64:67], v[136:139], v[204:207], v[64:67]
	v_mfma_f32_16x16x32_bf16 v[116:119], v[132:135], v[184:187], v[116:119]
	v_mfma_f32_16x16x32_bf16 v[108:111], v[140:143], v[184:187], v[108:111]
	v_mfma_f32_16x16x32_bf16 v[100:103], v[132:135], v[192:195], v[100:103]
	v_mfma_f32_16x16x32_bf16 v[92:95], v[140:143], v[192:195], v[92:95]
	v_mfma_f32_16x16x32_bf16 v[84:87], v[132:135], v[200:203], v[84:87]
	v_mfma_f32_16x16x32_bf16 v[76:79], v[140:143], v[200:203], v[76:79]
	v_mfma_f32_16x16x32_bf16 v[68:71], v[132:135], v[208:211], v[68:71]
	v_mfma_f32_16x16x32_bf16 v[64:67], v[140:143], v[208:211], v[64:67]
	s_setprio 0
	s_barrier
	s_and_b64 s[22:23], s[16:17], s[24:25]
	s_andn2_b64 vcc, exec, s[22:23]
	s_cbranch_vccnz .LBB0_723
	s_lshl_b32 s57, s47, 11
	s_lshl_b32 s58, s48, 11
	v_add_u32_e32 v164, s57, v247
	v_add_u32_e32 v168, s58, v247
	v_add_u32_e32 v166, 0x20000, v164
	v_add_u32_e32 v170, 0x20000, v168
	s_branch .LBB0_724
.LBB0_723:
.LBB0_724:
	s_add_u32 s22, s20, 0x100
	s_addc_u32 s23, s21, 0
	s_and_b64 s[52:53], s[24:25], exec
	s_cselect_b32 s0, 0, s22
	s_add_u32 s52, s49, s20
	s_addc_u32 s53, s50, s21
	s_and_b64 s[20:21], s[24:25], exec
	s_cselect_b32 s21, s15, s53
	s_cselect_b32 s20, s46, s52
	s_add_u32 s98, s2, s0
	s_addc_u32 s99, s3, s1
	s_mov_b32 m0, s28
	s_add_u32 s24, s20, 0x40000
	ds_read_b128 v[180:183], v179 offset:16384
	ds_read_b128 v[184:187], v179 offset:17408
	ds_read_b128 v[188:191], v179 offset:18432
	ds_read_b128 v[192:195], v179 offset:19456
	ds_read_b128 v[196:199], v179 offset:20480
	ds_read_b128 v[200:203], v179 offset:21504
	ds_read_b128 v[204:207], v179 offset:22528
	ds_read_b128 v[208:211], v179 offset:23552
	global_load_lds_dwordx4 v162, s[20:21]
	s_mov_b32 m0, s29
	s_addc_u32 s25, s21, 0
	global_load_lds_dwordx4 v160, s[20:21]
	s_mov_b32 m0, s30
	s_nop 0
	global_load_lds_dwordx4 v162, s[24:25]
	s_mov_b32 m0, s31
	s_nop 0
	global_load_lds_dwordx4 v160, s[24:25]
	s_mov_b32 m0, s27
	s_nop 0
	global_load_lds_dwordx4 v164, s[98:99]
	s_mov_b32 m0, s34
	s_nop 0
	global_load_lds_dwordx4 v166, s[98:99]
	s_waitcnt vmcnt(8)
	s_waitcnt lgkmcnt(0)
	s_barrier
	s_setprio 1
	s_waitcnt lgkmcnt(0)
	v_mfma_f32_16x16x32_bf16 v[60:63], v[144:147], v[180:183], v[60:63]
	v_mfma_f32_16x16x32_bf16 v[56:59], v[152:155], v[180:183], v[56:59]
	v_mfma_f32_16x16x32_bf16 v[48:51], v[144:147], v[188:191], v[48:51]
	v_mfma_f32_16x16x32_bf16 v[40:43], v[152:155], v[188:191], v[40:43]
	v_mfma_f32_16x16x32_bf16 v[32:35], v[144:147], v[196:199], v[32:35]
	v_mfma_f32_16x16x32_bf16 v[24:27], v[152:155], v[196:199], v[24:27]
	v_mfma_f32_16x16x32_bf16 v[16:19], v[144:147], v[204:207], v[16:19]
	v_mfma_f32_16x16x32_bf16 v[8:11], v[152:155], v[204:207], v[8:11]
	v_mfma_f32_16x16x32_bf16 v[60:63], v[148:151], v[184:187], v[60:63]
	v_mfma_f32_16x16x32_bf16 v[56:59], v[156:159], v[184:187], v[56:59]
	v_mfma_f32_16x16x32_bf16 v[48:51], v[148:151], v[192:195], v[48:51]
	v_mfma_f32_16x16x32_bf16 v[40:43], v[156:159], v[192:195], v[40:43]
	v_mfma_f32_16x16x32_bf16 v[32:35], v[148:151], v[200:203], v[32:35]
	v_mfma_f32_16x16x32_bf16 v[24:27], v[156:159], v[200:203], v[24:27]
	v_mfma_f32_16x16x32_bf16 v[16:19], v[148:151], v[208:211], v[16:19]
	v_mfma_f32_16x16x32_bf16 v[8:11], v[156:159], v[208:211], v[8:11]
	v_mfma_f32_16x16x32_bf16 v[52:55], v[128:131], v[180:183], v[52:55]
	v_mfma_f32_16x16x32_bf16 v[44:47], v[136:139], v[180:183], v[44:47]
	v_mfma_f32_16x16x32_bf16 v[36:39], v[128:131], v[188:191], v[36:39]
	v_mfma_f32_16x16x32_bf16 v[28:31], v[136:139], v[188:191], v[28:31]
	v_mfma_f32_16x16x32_bf16 v[20:23], v[128:131], v[196:199], v[20:23]
	v_mfma_f32_16x16x32_bf16 v[12:15], v[136:139], v[196:199], v[12:15]
	v_mfma_f32_16x16x32_bf16 v[4:7], v[128:131], v[204:207], v[4:7]
	v_mfma_f32_16x16x32_bf16 v[0:3], v[136:139], v[204:207], v[0:3]
	v_mfma_f32_16x16x32_bf16 v[52:55], v[132:135], v[184:187], v[52:55]
	v_mfma_f32_16x16x32_bf16 v[44:47], v[140:143], v[184:187], v[44:47]
	v_mfma_f32_16x16x32_bf16 v[36:39], v[132:135], v[192:195], v[36:39]
	v_mfma_f32_16x16x32_bf16 v[28:31], v[140:143], v[192:195], v[28:31]
	v_mfma_f32_16x16x32_bf16 v[20:23], v[132:135], v[200:203], v[20:23]
	v_mfma_f32_16x16x32_bf16 v[12:15], v[140:143], v[200:203], v[12:15]
	v_mfma_f32_16x16x32_bf16 v[4:7], v[132:135], v[208:211], v[4:7]
	v_mfma_f32_16x16x32_bf16 v[0:3], v[140:143], v[208:211], v[0:3]
	s_setprio 0
	s_barrier
	s_add_i32 s24, 0, 0x18000
	s_add_i32 s25, 0, 0x1c000
	v_add_u32_e32 v140, s24, v176
	v_add_u32_e32 v156, s25, v176
	ds_read_b128 v[128:131], v140
	ds_read_b128 v[132:135], v140 offset:1024
	ds_read_b128 v[136:139], v140 offset:2048
	ds_read_b128 v[140:143], v140 offset:3072
	ds_read_b128 v[144:147], v156
	ds_read_b128 v[148:151], v156 offset:1024
	ds_read_b128 v[152:155], v156 offset:2048
	ds_read_b128 v[156:159], v156 offset:3072
	s_mov_b32 m0, s35
	ds_read_b128 v[180:183], v179 offset:32768
	ds_read_b128 v[184:187], v179 offset:33792
	ds_read_b128 v[188:191], v179 offset:34816
	ds_read_b128 v[192:195], v179 offset:35840
	ds_read_b128 v[196:199], v179 offset:36864
	ds_read_b128 v[200:203], v179 offset:37888
	ds_read_b128 v[204:207], v179 offset:38912
	ds_read_b128 v[208:211], v179 offset:39936
	global_load_lds_dwordx4 v168, s[98:99]
	s_mov_b32 m0, s36
	s_nop 0
	global_load_lds_dwordx4 v170, s[98:99]
	s_waitcnt vmcnt(8)
	s_waitcnt lgkmcnt(0)
	s_barrier
	s_setprio 1
	s_waitcnt lgkmcnt(0)
	v_mfma_f32_16x16x32_bf16 v[124:127], v[128:131], v[180:183], v[124:127]
	v_mfma_f32_16x16x32_bf16 v[120:123], v[136:139], v[180:183], v[120:123]
	v_mfma_f32_16x16x32_bf16 v[112:115], v[128:131], v[188:191], v[112:115]
	v_mfma_f32_16x16x32_bf16 v[104:107], v[136:139], v[188:191], v[104:107]
	v_mfma_f32_16x16x32_bf16 v[96:99], v[128:131], v[196:199], v[96:99]
	v_mfma_f32_16x16x32_bf16 v[88:91], v[136:139], v[196:199], v[88:91]
	v_mfma_f32_16x16x32_bf16 v[80:83], v[128:131], v[204:207], v[80:83]
	v_mfma_f32_16x16x32_bf16 v[72:75], v[136:139], v[204:207], v[72:75]
	v_mfma_f32_16x16x32_bf16 v[124:127], v[132:135], v[184:187], v[124:127]
	v_mfma_f32_16x16x32_bf16 v[120:123], v[140:143], v[184:187], v[120:123]
	v_mfma_f32_16x16x32_bf16 v[112:115], v[132:135], v[192:195], v[112:115]
	v_mfma_f32_16x16x32_bf16 v[104:107], v[140:143], v[192:195], v[104:107]
	v_mfma_f32_16x16x32_bf16 v[96:99], v[132:135], v[200:203], v[96:99]
	v_mfma_f32_16x16x32_bf16 v[88:91], v[140:143], v[200:203], v[88:91]
	v_mfma_f32_16x16x32_bf16 v[80:83], v[132:135], v[208:211], v[80:83]
	v_mfma_f32_16x16x32_bf16 v[72:75], v[140:143], v[208:211], v[72:75]
	v_mfma_f32_16x16x32_bf16 v[116:119], v[144:147], v[180:183], v[116:119]
	v_mfma_f32_16x16x32_bf16 v[108:111], v[152:155], v[180:183], v[108:111]
	v_mfma_f32_16x16x32_bf16 v[100:103], v[144:147], v[188:191], v[100:103]
	v_mfma_f32_16x16x32_bf16 v[92:95], v[152:155], v[188:191], v[92:95]
	v_mfma_f32_16x16x32_bf16 v[84:87], v[144:147], v[196:199], v[84:87]
	v_mfma_f32_16x16x32_bf16 v[76:79], v[152:155], v[196:199], v[76:79]
	v_mfma_f32_16x16x32_bf16 v[68:71], v[144:147], v[204:207], v[68:71]
	v_mfma_f32_16x16x32_bf16 v[64:67], v[152:155], v[204:207], v[64:67]
	v_mfma_f32_16x16x32_bf16 v[116:119], v[148:151], v[184:187], v[116:119]
	v_mfma_f32_16x16x32_bf16 v[108:111], v[156:159], v[184:187], v[108:111]
	v_mfma_f32_16x16x32_bf16 v[100:103], v[148:151], v[192:195], v[100:103]
	v_mfma_f32_16x16x32_bf16 v[92:95], v[156:159], v[192:195], v[92:95]
	v_mfma_f32_16x16x32_bf16 v[84:87], v[148:151], v[200:203], v[84:87]
	v_mfma_f32_16x16x32_bf16 v[76:79], v[156:159], v[200:203], v[76:79]
	v_mfma_f32_16x16x32_bf16 v[68:71], v[148:151], v[208:211], v[68:71]
	v_mfma_f32_16x16x32_bf16 v[64:67], v[156:159], v[208:211], v[64:67]
	s_setprio 0
	s_barrier
	s_add_i32 s0, s24, s84
	s_add_u32 s100, s20, s6
	s_addc_u32 s101, s21, s7
	s_add_u32 s98, s98, s6
	s_addc_u32 s99, s99, s7
	s_mov_b32 m0, s0
	ds_read_b128 v[180:183], v179 offset:49152
	ds_read_b128 v[184:187], v179 offset:50176
	ds_read_b128 v[188:191], v179 offset:51200
	ds_read_b128 v[192:195], v179 offset:52224
	ds_read_b128 v[196:199], v179 offset:53248
	ds_read_b128 v[200:203], v179 offset:54272
	ds_read_b128 v[204:207], v179 offset:55296
	ds_read_b128 v[208:211], v179 offset:56320
	global_load_lds_dwordx4 v162, s[100:101]
	s_add_i32 m0, s0, 0x2000
	s_add_u32 s20, s20, 0x40080
	s_addc_u32 s21, s21, 0
	s_add_i32 s0, s25, s84
	global_load_lds_dwordx4 v160, s[100:101]
	s_mov_b32 m0, s0
	s_nop 0
	global_load_lds_dwordx4 v162, s[20:21]
	s_add_i32 m0, s0, 0x2000
	s_nop 0
	global_load_lds_dwordx4 v160, s[20:21]
	s_mov_b32 m0, s37
	s_nop 0
	global_load_lds_dwordx4 v164, s[98:99]
	s_mov_b32 m0, s38
	s_nop 0
	global_load_lds_dwordx4 v166, s[98:99]
	s_waitcnt vmcnt(8)
	s_waitcnt lgkmcnt(0)
	s_barrier
	s_setprio 1
	s_waitcnt lgkmcnt(0)
	v_mfma_f32_16x16x32_bf16 v[60:63], v[128:131], v[180:183], v[60:63]
	v_mfma_f32_16x16x32_bf16 v[56:59], v[136:139], v[180:183], v[56:59]
	v_mfma_f32_16x16x32_bf16 v[48:51], v[128:131], v[188:191], v[48:51]
	v_mfma_f32_16x16x32_bf16 v[40:43], v[136:139], v[188:191], v[40:43]
	v_mfma_f32_16x16x32_bf16 v[32:35], v[128:131], v[196:199], v[32:35]
	v_mfma_f32_16x16x32_bf16 v[24:27], v[136:139], v[196:199], v[24:27]
	v_mfma_f32_16x16x32_bf16 v[16:19], v[128:131], v[204:207], v[16:19]
	v_mfma_f32_16x16x32_bf16 v[8:11], v[136:139], v[204:207], v[8:11]
	v_mfma_f32_16x16x32_bf16 v[60:63], v[132:135], v[184:187], v[60:63]
	v_mfma_f32_16x16x32_bf16 v[56:59], v[140:143], v[184:187], v[56:59]
	v_mfma_f32_16x16x32_bf16 v[48:51], v[132:135], v[192:195], v[48:51]
	v_mfma_f32_16x16x32_bf16 v[40:43], v[140:143], v[192:195], v[40:43]
	v_mfma_f32_16x16x32_bf16 v[32:35], v[132:135], v[200:203], v[32:35]
	v_mfma_f32_16x16x32_bf16 v[24:27], v[140:143], v[200:203], v[24:27]
	v_mfma_f32_16x16x32_bf16 v[16:19], v[132:135], v[208:211], v[16:19]
	v_mfma_f32_16x16x32_bf16 v[8:11], v[140:143], v[208:211], v[8:11]
	v_mfma_f32_16x16x32_bf16 v[52:55], v[144:147], v[180:183], v[52:55]
	v_mfma_f32_16x16x32_bf16 v[44:47], v[152:155], v[180:183], v[44:47]
	v_mfma_f32_16x16x32_bf16 v[36:39], v[144:147], v[188:191], v[36:39]
	v_mfma_f32_16x16x32_bf16 v[28:31], v[152:155], v[188:191], v[28:31]
	v_mfma_f32_16x16x32_bf16 v[20:23], v[144:147], v[196:199], v[20:23]
	v_mfma_f32_16x16x32_bf16 v[12:15], v[152:155], v[196:199], v[12:15]
	v_mfma_f32_16x16x32_bf16 v[4:7], v[144:147], v[204:207], v[4:7]
	v_mfma_f32_16x16x32_bf16 v[0:3], v[152:155], v[204:207], v[0:3]
	v_mfma_f32_16x16x32_bf16 v[52:55], v[148:151], v[184:187], v[52:55]
	v_mfma_f32_16x16x32_bf16 v[44:47], v[156:159], v[184:187], v[44:47]
	v_mfma_f32_16x16x32_bf16 v[36:39], v[148:151], v[192:195], v[36:39]
	v_mfma_f32_16x16x32_bf16 v[28:31], v[156:159], v[192:195], v[28:31]
	v_mfma_f32_16x16x32_bf16 v[20:23], v[148:151], v[200:203], v[20:23]
	v_mfma_f32_16x16x32_bf16 v[12:15], v[156:159], v[200:203], v[12:15]
	v_mfma_f32_16x16x32_bf16 v[4:7], v[148:151], v[208:211], v[4:7]
	v_mfma_f32_16x16x32_bf16 v[0:3], v[156:159], v[208:211], v[0:3]
	s_setprio 0
	s_barrier
	s_add_i32 s51, s51, 2
	s_cmp_gt_u32 s51, 13
	s_cbranch_scc1 .LBB0_726
	s_mov_b64 s[20:21], s[22:23]
	s_branch .LBB0_721

.Lgu_noidx:
	ds_read_b128 v[16:19], v177
	ds_read_b128 v[20:23], v177 offset:1024
	ds_read_b128 v[24:27], v177 offset:2048
	ds_read_b128 v[28:31], v177 offset:3072
	ds_read_b128 v[0:3], v178
	ds_read_b128 v[4:7], v178 offset:1024
	ds_read_b128 v[8:11], v178 offset:2048
	ds_read_b128 v[12:15], v178 offset:3072
	s_cmp_eq_u32 s57, 4
	s_cselect_b64 s[26:27], -1, 0
	s_add_u32 s24, s40, s22
	s_addc_u32 s25, s41, s23
	s_mov_b32 m0, s43
	ds_read_b128 v[180:183], v179
	ds_read_b128 v[184:187], v179 offset:1024
	ds_read_b128 v[188:191], v179 offset:2048
	ds_read_b128 v[192:195], v179 offset:3072
	ds_read_b128 v[196:199], v179 offset:4096
	ds_read_b128 v[200:203], v179 offset:5120
	ds_read_b128 v[204:207], v179 offset:6144
	ds_read_b128 v[208:211], v179 offset:7168
	global_load_lds_dwordx4 v168, s[24:25]
	s_mov_b32 m0, s44
	s_nop 0
	global_load_lds_dwordx4 v166, s[24:25]
	s_waitcnt vmcnt(8)
	s_waitcnt lgkmcnt(0)
	s_barrier
	s_setprio 1
	s_waitcnt lgkmcnt(0)
	v_mfma_f32_16x16x128_f8f6f4 v[156:159], v[16:23], v[180:187], 0
	v_mfma_f32_16x16x128_f8f6f4 v[152:155], v[24:31], v[180:187], 0
	v_mfma_f32_16x16x128_f8f6f4 v[140:143], v[16:23], v[188:195], 0
	v_mfma_f32_16x16x128_f8f6f4 v[136:139], v[24:31], v[188:195], 0
	v_mfma_f32_16x16x128_f8f6f4 v[124:127], v[16:23], v[196:203], 0
	v_mfma_f32_16x16x128_f8f6f4 v[120:123], v[24:31], v[196:203], 0
	v_mfma_f32_16x16x128_f8f6f4 v[108:111], v[16:23], v[204:211], 0
	v_mfma_f32_16x16x128_f8f6f4 v[104:107], v[24:31], v[204:211], 0
	v_mfma_f32_16x16x128_f8f6f4 v[148:151], v[0:7], v[180:187], 0
	v_mfma_f32_16x16x128_f8f6f4 v[144:147], v[8:15], v[180:187], 0
	v_mfma_f32_16x16x128_f8f6f4 v[132:135], v[0:7], v[188:195], 0
	v_mfma_f32_16x16x128_f8f6f4 v[128:131], v[8:15], v[188:195], 0
	v_mfma_f32_16x16x128_f8f6f4 v[116:119], v[0:7], v[196:203], 0
	v_mfma_f32_16x16x128_f8f6f4 v[112:115], v[8:15], v[196:203], 0
	v_mfma_f32_16x16x128_f8f6f4 v[100:103], v[0:7], v[204:211], 0
	v_mfma_f32_16x16x128_f8f6f4 v[96:99], v[8:15], v[204:211], 0
	s_setprio 0
	s_barrier
	s_and_b64 s[24:25], s[18:19], s[26:27]
	s_andn2_b64 vcc, exec, s[24:25]
	s_cbranch_vccnz .Lpk2_LBB0_1250
	v_lshl_add_u32 v164, v248, 10, v252
	v_lshl_add_u32 v170, v249, 10, v252
	v_lshl_add_u32 v168, v250, 10, v252
	v_lshl_add_u32 v166, v251, 10, v252
	s_branch .Lpk2_LBB0_1251
.Lpk2_LBB0_1250:
.Lpk2_LBB0_1251:
	s_add_u32 s24, s22, 0x100
	s_addc_u32 s25, s23, 0
	s_and_b64 s[70:71], s[26:27], exec
	s_cselect_b32 s6, 0, s24
	s_add_u32 s70, s53, s22
	s_addc_u32 s71, s56, s23
	s_and_b64 s[22:23], s[26:27], exec
	s_cselect_b32 s23, s17, s71
	s_cselect_b32 s22, s50, s70
	s_add_u32 s98, s4, s6
	s_addc_u32 s99, s5, s7
	s_mov_b32 m0, s29
	s_add_u32 s26, s22, 0x20000
	ds_read_b128 v[180:183], v179 offset:16384
	ds_read_b128 v[184:187], v179 offset:17408
	ds_read_b128 v[188:191], v179 offset:18432
	ds_read_b128 v[192:195], v179 offset:19456
	ds_read_b128 v[196:199], v179 offset:20480
	ds_read_b128 v[200:203], v179 offset:21504
	ds_read_b128 v[204:207], v179 offset:22528
	ds_read_b128 v[208:211], v179 offset:23552
	global_load_lds_dwordx4 v162, s[22:23]
	s_mov_b32 m0, s30
	s_addc_u32 s27, s23, 0
	global_load_lds_dwordx4 v160, s[22:23]
	s_mov_b32 m0, s31
	s_nop 0
	global_load_lds_dwordx4 v162, s[26:27]
	s_mov_b32 m0, s34
	s_nop 0
	global_load_lds_dwordx4 v160, s[26:27]
	s_mov_b32 m0, s28
	s_nop 0
	global_load_lds_dwordx4 v164, s[98:99]
	s_mov_b32 m0, s35
	s_nop 0
	global_load_lds_dwordx4 v170, s[98:99]
	s_waitcnt vmcnt(8)
	s_waitcnt lgkmcnt(0)
	s_barrier
	s_setprio 1
	s_waitcnt lgkmcnt(0)
	v_mfma_f32_16x16x128_f8f6f4 v[92:95], v[16:23], v[180:187], 0
	v_mfma_f32_16x16x128_f8f6f4 v[88:91], v[24:31], v[180:187], 0
	v_mfma_f32_16x16x128_f8f6f4 v[76:79], v[16:23], v[188:195], 0
	v_mfma_f32_16x16x128_f8f6f4 v[72:75], v[24:31], v[188:195], 0
	v_mfma_f32_16x16x128_f8f6f4 v[212:215], v[16:23], v[196:203], 0
	v_mfma_f32_16x16x128_f8f6f4 v[216:219], v[24:31], v[196:203], 0
	v_mfma_f32_16x16x128_f8f6f4 v[220:223], v[16:23], v[204:211], 0
	v_mfma_f32_16x16x128_f8f6f4 v[224:227], v[24:31], v[204:211], 0
	v_mfma_f32_16x16x128_f8f6f4 v[84:87], v[0:7], v[180:187], 0
	v_mfma_f32_16x16x128_f8f6f4 v[80:83], v[8:15], v[180:187], 0
	v_mfma_f32_16x16x128_f8f6f4 v[68:71], v[0:7], v[188:195], 0
	v_mfma_f32_16x16x128_f8f6f4 v[64:67], v[8:15], v[188:195], 0
	v_mfma_f32_16x16x128_f8f6f4 v[228:231], v[0:7], v[196:203], 0
	v_mfma_f32_16x16x128_f8f6f4 v[196:199], v[8:15], v[196:203], 0
	v_mfma_f32_16x16x128_f8f6f4 v[200:203], v[0:7], v[204:211], 0
	v_mfma_f32_16x16x128_f8f6f4 v[204:207], v[8:15], v[204:211], 0
	s_setprio 0
	s_barrier
	s_add_i32 s26, 0, 0x18000
	s_add_i32 s27, 0, 0x1c000
	v_add_u32_e32 v12, s26, v176
	v_add_u32_e32 v28, s27, v176
	ds_read_b128 v[0:3], v12
	ds_read_b128 v[4:7], v12 offset:1024
	ds_read_b128 v[8:11], v12 offset:2048
	ds_read_b128 v[12:15], v12 offset:3072
	ds_read_b128 v[16:19], v28
	ds_read_b128 v[20:23], v28 offset:1024
	ds_read_b128 v[24:27], v28 offset:2048
	ds_read_b128 v[28:31], v28 offset:3072
	s_mov_b32 m0, s36
	ds_read_b128 v[32:35], v179 offset:32768
	ds_read_b128 v[36:39], v179 offset:33792
	ds_read_b128 v[40:43], v179 offset:34816
	ds_read_b128 v[44:47], v179 offset:35840
	ds_read_b128 v[48:51], v179 offset:36864
	ds_read_b128 v[52:55], v179 offset:37888
	ds_read_b128 v[56:59], v179 offset:38912
	ds_read_b128 v[60:63], v179 offset:39936
	global_load_lds_dwordx4 v168, s[98:99]
	s_mov_b32 m0, s37
	s_nop 0
	global_load_lds_dwordx4 v166, s[98:99]
	s_waitcnt vmcnt(8)
	s_waitcnt lgkmcnt(0)
	s_barrier
	s_setprio 1
	s_waitcnt lgkmcnt(0)
	v_mfma_f32_16x16x128_f8f6f4 v[156:159], v[0:7], v[32:39], v[156:159]
	v_mfma_f32_16x16x128_f8f6f4 v[152:155], v[8:15], v[32:39], v[152:155]
	v_mfma_f32_16x16x128_f8f6f4 v[140:143], v[0:7], v[40:47], v[140:143]
	v_mfma_f32_16x16x128_f8f6f4 v[136:139], v[8:15], v[40:47], v[136:139]
	v_mfma_f32_16x16x128_f8f6f4 v[124:127], v[0:7], v[48:55], v[124:127]
	v_mfma_f32_16x16x128_f8f6f4 v[120:123], v[8:15], v[48:55], v[120:123]
	v_mfma_f32_16x16x128_f8f6f4 v[108:111], v[0:7], v[56:63], v[108:111]
	v_mfma_f32_16x16x128_f8f6f4 v[104:107], v[8:15], v[56:63], v[104:107]
	v_mfma_f32_16x16x128_f8f6f4 v[148:151], v[16:23], v[32:39], v[148:151]
	v_mfma_f32_16x16x128_f8f6f4 v[144:147], v[24:31], v[32:39], v[144:147]
	v_mfma_f32_16x16x128_f8f6f4 v[132:135], v[16:23], v[40:47], v[132:135]
	v_mfma_f32_16x16x128_f8f6f4 v[128:131], v[24:31], v[40:47], v[128:131]
	v_mfma_f32_16x16x128_f8f6f4 v[116:119], v[16:23], v[48:55], v[116:119]
	v_mfma_f32_16x16x128_f8f6f4 v[112:115], v[24:31], v[48:55], v[112:115]
	v_mfma_f32_16x16x128_f8f6f4 v[100:103], v[16:23], v[56:63], v[100:103]
	v_mfma_f32_16x16x128_f8f6f4 v[96:99], v[24:31], v[56:63], v[96:99]
	s_setprio 0
	s_barrier
	s_add_i32 s6, s26, s84
	s_add_u32 s100, s22, s10
	s_addc_u32 s101, s23, s11
	s_add_u32 s98, s98, s10
	s_addc_u32 s99, s99, s11
	s_mov_b32 m0, s6
	ds_read_b128 v[32:35], v179 offset:49152
	ds_read_b128 v[36:39], v179 offset:50176
	ds_read_b128 v[48:51], v179 offset:51200
	ds_read_b128 v[52:55], v179 offset:52224
	ds_read_b128 v[180:183], v179 offset:53248
	ds_read_b128 v[184:187], v179 offset:54272
	ds_read_b128 v[188:191], v179 offset:55296
	ds_read_b128 v[192:195], v179 offset:56320
	global_load_lds_dwordx4 v162, s[100:101]
	s_add_i32 m0, s6, 0x2000
	s_add_u32 s22, s22, 0x20080
	s_addc_u32 s23, s23, 0
	s_add_i32 s6, s27, s84
	global_load_lds_dwordx4 v160, s[100:101]
	s_mov_b32 m0, s6
	s_nop 0
	global_load_lds_dwordx4 v162, s[22:23]
	s_add_i32 m0, s6, 0x2000
	s_nop 0
	global_load_lds_dwordx4 v160, s[22:23]
	s_mov_b32 m0, s38
	s_nop 0
	global_load_lds_dwordx4 v164, s[98:99]
	s_mov_b32 m0, s39
	s_nop 0
	global_load_lds_dwordx4 v170, s[98:99]
	s_waitcnt vmcnt(8)
	s_waitcnt lgkmcnt(0)
	s_barrier
	s_setprio 1
	s_waitcnt lgkmcnt(0)
	v_mfma_f32_16x16x128_f8f6f4 v[92:95], v[0:7], v[32:39], v[92:95]
	v_mfma_f32_16x16x128_f8f6f4 v[88:91], v[8:15], v[32:39], v[88:91]
	v_mfma_f32_16x16x128_f8f6f4 v[76:79], v[0:7], v[48:55], v[76:79]
	v_mfma_f32_16x16x128_f8f6f4 v[72:75], v[8:15], v[48:55], v[72:75]
	v_mfma_f32_16x16x128_f8f6f4 v[60:63], v[0:7], v[180:187], v[212:215]
	v_mfma_f32_16x16x128_f8f6f4 v[56:59], v[8:15], v[180:187], v[216:219]
	v_mfma_f32_16x16x128_f8f6f4 v[44:47], v[0:7], v[188:195], v[220:223]
	v_mfma_f32_16x16x128_f8f6f4 v[40:43], v[8:15], v[188:195], v[224:227]
	v_mfma_f32_16x16x128_f8f6f4 v[84:87], v[16:23], v[32:39], v[84:87]
	v_mfma_f32_16x16x128_f8f6f4 v[80:83], v[24:31], v[32:39], v[80:83]
	v_mfma_f32_16x16x128_f8f6f4 v[68:71], v[16:23], v[48:55], v[68:71]
	v_mfma_f32_16x16x128_f8f6f4 v[64:67], v[24:31], v[48:55], v[64:67]
	v_mfma_f32_16x16x128_f8f6f4 v[52:55], v[16:23], v[180:187], v[228:231]
	v_mfma_f32_16x16x128_f8f6f4 v[48:51], v[24:31], v[180:187], v[196:199]
	v_mfma_f32_16x16x128_f8f6f4 v[36:39], v[16:23], v[188:195], v[200:203]
	v_mfma_f32_16x16x128_f8f6f4 v[32:35], v[24:31], v[188:195], v[204:207]
	s_setprio 0
	s_barrier
	s_add_i32 s57, s57, 2
	s_cmp_gt_u32 s57, 5
	s_cbranch_scc1 .LBB0_1253
	s_mov_b64 s[22:23], s[24:25]
	s_branch .LBB0_1248
.LBB0_1248:
	ds_read_b128 v[16:19], v177
	ds_read_b128 v[20:23], v177 offset:1024
	ds_read_b128 v[24:27], v177 offset:2048
	ds_read_b128 v[28:31], v177 offset:3072
	ds_read_b128 v[0:3], v178
	ds_read_b128 v[4:7], v178 offset:1024
	ds_read_b128 v[8:11], v178 offset:2048
	ds_read_b128 v[12:15], v178 offset:3072
	s_cmp_eq_u32 s57, 4
	s_cselect_b64 s[26:27], -1, 0
	s_add_u32 s24, s40, s22
	s_addc_u32 s25, s41, s23
	s_mov_b32 m0, s43
	ds_read_b128 v[180:183], v179
	ds_read_b128 v[184:187], v179 offset:1024
	ds_read_b128 v[188:191], v179 offset:2048
	ds_read_b128 v[192:195], v179 offset:3072
	ds_read_b128 v[196:199], v179 offset:4096
	ds_read_b128 v[200:203], v179 offset:5120
	ds_read_b128 v[204:207], v179 offset:6144
	ds_read_b128 v[208:211], v179 offset:7168
	global_load_lds_dwordx4 v168, s[24:25]
	s_mov_b32 m0, s44
	s_nop 0
	global_load_lds_dwordx4 v166, s[24:25]
	s_waitcnt vmcnt(8)
	s_waitcnt lgkmcnt(0)
	s_barrier
	s_setprio 1
	s_waitcnt lgkmcnt(0)
	v_mfma_f32_16x16x128_f8f6f4 v[156:159], v[16:23], v[180:187], v[156:159]
	v_mfma_f32_16x16x128_f8f6f4 v[152:155], v[24:31], v[180:187], v[152:155]
	v_mfma_f32_16x16x128_f8f6f4 v[140:143], v[16:23], v[188:195], v[140:143]
	v_mfma_f32_16x16x128_f8f6f4 v[136:139], v[24:31], v[188:195], v[136:139]
	v_mfma_f32_16x16x128_f8f6f4 v[124:127], v[16:23], v[196:203], v[124:127]
	v_mfma_f32_16x16x128_f8f6f4 v[120:123], v[24:31], v[196:203], v[120:123]
	v_mfma_f32_16x16x128_f8f6f4 v[108:111], v[16:23], v[204:211], v[108:111]
	v_mfma_f32_16x16x128_f8f6f4 v[104:107], v[24:31], v[204:211], v[104:107]
	v_mfma_f32_16x16x128_f8f6f4 v[148:151], v[0:7], v[180:187], v[148:151]
	v_mfma_f32_16x16x128_f8f6f4 v[144:147], v[8:15], v[180:187], v[144:147]
	v_mfma_f32_16x16x128_f8f6f4 v[132:135], v[0:7], v[188:195], v[132:135]
	v_mfma_f32_16x16x128_f8f6f4 v[128:131], v[8:15], v[188:195], v[128:131]
	v_mfma_f32_16x16x128_f8f6f4 v[116:119], v[0:7], v[196:203], v[116:119]
	v_mfma_f32_16x16x128_f8f6f4 v[112:115], v[8:15], v[196:203], v[112:115]
	v_mfma_f32_16x16x128_f8f6f4 v[100:103], v[0:7], v[204:211], v[100:103]
	v_mfma_f32_16x16x128_f8f6f4 v[96:99], v[8:15], v[204:211], v[96:99]
	s_setprio 0
	s_barrier
	s_and_b64 s[24:25], s[18:19], s[26:27]
	s_andn2_b64 vcc, exec, s[24:25]
	s_cbranch_vccnz .LBB0_1250
	v_lshl_add_u32 v164, v248, 10, v252
	v_lshl_add_u32 v170, v249, 10, v252
	v_lshl_add_u32 v168, v250, 10, v252
	v_lshl_add_u32 v166, v251, 10, v252
	s_branch .LBB0_1251
.LBB0_1250:
.LBB0_1251:
	s_add_u32 s24, s22, 0x100
	s_addc_u32 s25, s23, 0
	s_and_b64 s[70:71], s[26:27], exec
	s_cselect_b32 s6, 0, s24
	s_add_u32 s70, s53, s22
	s_addc_u32 s71, s56, s23
	s_and_b64 s[22:23], s[26:27], exec
	s_cselect_b32 s23, s17, s71
	s_cselect_b32 s22, s50, s70
	s_add_u32 s98, s4, s6
	s_addc_u32 s99, s5, s7
	s_mov_b32 m0, s29
	s_add_u32 s26, s22, 0x20000
	ds_read_b128 v[180:183], v179 offset:16384
	ds_read_b128 v[184:187], v179 offset:17408
	ds_read_b128 v[188:191], v179 offset:18432
	ds_read_b128 v[192:195], v179 offset:19456
	ds_read_b128 v[196:199], v179 offset:20480
	ds_read_b128 v[200:203], v179 offset:21504
	ds_read_b128 v[204:207], v179 offset:22528
	ds_read_b128 v[208:211], v179 offset:23552
	global_load_lds_dwordx4 v162, s[22:23]
	s_mov_b32 m0, s30
	s_addc_u32 s27, s23, 0
	global_load_lds_dwordx4 v160, s[22:23]
	s_mov_b32 m0, s31
	s_nop 0
	global_load_lds_dwordx4 v162, s[26:27]
	s_mov_b32 m0, s34
	s_nop 0
	global_load_lds_dwordx4 v160, s[26:27]
	s_mov_b32 m0, s28
	s_nop 0
	global_load_lds_dwordx4 v164, s[98:99]
	s_mov_b32 m0, s35
	s_nop 0
	global_load_lds_dwordx4 v170, s[98:99]
	s_waitcnt vmcnt(8)
	s_waitcnt lgkmcnt(0)
	s_barrier
	s_setprio 1
	s_waitcnt lgkmcnt(0)
	v_mfma_f32_16x16x128_f8f6f4 v[92:95], v[16:23], v[180:187], v[92:95]
	v_mfma_f32_16x16x128_f8f6f4 v[88:91], v[24:31], v[180:187], v[88:91]
	v_mfma_f32_16x16x128_f8f6f4 v[76:79], v[16:23], v[188:195], v[76:79]
	v_mfma_f32_16x16x128_f8f6f4 v[72:75], v[24:31], v[188:195], v[72:75]
	v_mfma_f32_16x16x128_f8f6f4 v[212:215], v[16:23], v[196:203], v[60:63]
	v_mfma_f32_16x16x128_f8f6f4 v[216:219], v[24:31], v[196:203], v[56:59]
	v_mfma_f32_16x16x128_f8f6f4 v[220:223], v[16:23], v[204:211], v[44:47]
	v_mfma_f32_16x16x128_f8f6f4 v[224:227], v[24:31], v[204:211], v[40:43]
	v_mfma_f32_16x16x128_f8f6f4 v[84:87], v[0:7], v[180:187], v[84:87]
	v_mfma_f32_16x16x128_f8f6f4 v[80:83], v[8:15], v[180:187], v[80:83]
	v_mfma_f32_16x16x128_f8f6f4 v[68:71], v[0:7], v[188:195], v[68:71]
	v_mfma_f32_16x16x128_f8f6f4 v[64:67], v[8:15], v[188:195], v[64:67]
	v_mfma_f32_16x16x128_f8f6f4 v[228:231], v[0:7], v[196:203], v[52:55]
	v_mfma_f32_16x16x128_f8f6f4 v[196:199], v[8:15], v[196:203], v[48:51]
	v_mfma_f32_16x16x128_f8f6f4 v[200:203], v[0:7], v[204:211], v[36:39]
	v_mfma_f32_16x16x128_f8f6f4 v[204:207], v[8:15], v[204:211], v[32:35]
	s_setprio 0
	s_barrier
	s_add_i32 s26, 0, 0x18000
	s_add_i32 s27, 0, 0x1c000
	v_add_u32_e32 v12, s26, v176
	v_add_u32_e32 v28, s27, v176
	ds_read_b128 v[0:3], v12
	ds_read_b128 v[4:7], v12 offset:1024
	ds_read_b128 v[8:11], v12 offset:2048
	ds_read_b128 v[12:15], v12 offset:3072
	ds_read_b128 v[16:19], v28
	ds_read_b128 v[20:23], v28 offset:1024
	ds_read_b128 v[24:27], v28 offset:2048
	ds_read_b128 v[28:31], v28 offset:3072
	s_mov_b32 m0, s36
	ds_read_b128 v[32:35], v179 offset:32768
	ds_read_b128 v[36:39], v179 offset:33792
	ds_read_b128 v[40:43], v179 offset:34816
	ds_read_b128 v[44:47], v179 offset:35840
	ds_read_b128 v[48:51], v179 offset:36864
	ds_read_b128 v[52:55], v179 offset:37888
	ds_read_b128 v[56:59], v179 offset:38912
	ds_read_b128 v[60:63], v179 offset:39936
	global_load_lds_dwordx4 v168, s[98:99]
	s_mov_b32 m0, s37
	s_nop 0
	global_load_lds_dwordx4 v166, s[98:99]
	s_waitcnt vmcnt(8)
	s_waitcnt lgkmcnt(0)
	s_barrier
	s_setprio 1
	s_waitcnt lgkmcnt(0)
	v_mfma_f32_16x16x128_f8f6f4 v[156:159], v[0:7], v[32:39], v[156:159]
	v_mfma_f32_16x16x128_f8f6f4 v[152:155], v[8:15], v[32:39], v[152:155]
	v_mfma_f32_16x16x128_f8f6f4 v[140:143], v[0:7], v[40:47], v[140:143]
	v_mfma_f32_16x16x128_f8f6f4 v[136:139], v[8:15], v[40:47], v[136:139]
	v_mfma_f32_16x16x128_f8f6f4 v[124:127], v[0:7], v[48:55], v[124:127]
	v_mfma_f32_16x16x128_f8f6f4 v[120:123], v[8:15], v[48:55], v[120:123]
	v_mfma_f32_16x16x128_f8f6f4 v[108:111], v[0:7], v[56:63], v[108:111]
	v_mfma_f32_16x16x128_f8f6f4 v[104:107], v[8:15], v[56:63], v[104:107]
	v_mfma_f32_16x16x128_f8f6f4 v[148:151], v[16:23], v[32:39], v[148:151]
	v_mfma_f32_16x16x128_f8f6f4 v[144:147], v[24:31], v[32:39], v[144:147]
	v_mfma_f32_16x16x128_f8f6f4 v[132:135], v[16:23], v[40:47], v[132:135]
	v_mfma_f32_16x16x128_f8f6f4 v[128:131], v[24:31], v[40:47], v[128:131]
	v_mfma_f32_16x16x128_f8f6f4 v[116:119], v[16:23], v[48:55], v[116:119]
	v_mfma_f32_16x16x128_f8f6f4 v[112:115], v[24:31], v[48:55], v[112:115]
	v_mfma_f32_16x16x128_f8f6f4 v[100:103], v[16:23], v[56:63], v[100:103]
	v_mfma_f32_16x16x128_f8f6f4 v[96:99], v[24:31], v[56:63], v[96:99]
	s_setprio 0
	s_barrier
	s_add_i32 s6, s26, s84
	s_add_u32 s100, s22, s10
	s_addc_u32 s101, s23, s11
	s_add_u32 s98, s98, s10
	s_addc_u32 s99, s99, s11
	s_mov_b32 m0, s6
	ds_read_b128 v[32:35], v179 offset:49152
	ds_read_b128 v[36:39], v179 offset:50176
	ds_read_b128 v[48:51], v179 offset:51200
	ds_read_b128 v[52:55], v179 offset:52224
	ds_read_b128 v[180:183], v179 offset:53248
	ds_read_b128 v[184:187], v179 offset:54272
	ds_read_b128 v[188:191], v179 offset:55296
	ds_read_b128 v[192:195], v179 offset:56320
	global_load_lds_dwordx4 v162, s[100:101]
	s_add_i32 m0, s6, 0x2000
	s_add_u32 s22, s22, 0x20080
	s_addc_u32 s23, s23, 0
	s_add_i32 s6, s27, s84
	global_load_lds_dwordx4 v160, s[100:101]
	s_mov_b32 m0, s6
	s_nop 0
	global_load_lds_dwordx4 v162, s[22:23]
	s_add_i32 m0, s6, 0x2000
	s_nop 0
	global_load_lds_dwordx4 v160, s[22:23]
	s_mov_b32 m0, s38
	s_nop 0
	global_load_lds_dwordx4 v164, s[98:99]
	s_mov_b32 m0, s39
	s_nop 0
	global_load_lds_dwordx4 v170, s[98:99]
	s_waitcnt vmcnt(8)
	s_waitcnt lgkmcnt(0)
	s_barrier
	s_setprio 1
	s_waitcnt lgkmcnt(0)
	v_mfma_f32_16x16x128_f8f6f4 v[92:95], v[0:7], v[32:39], v[92:95]
	v_mfma_f32_16x16x128_f8f6f4 v[88:91], v[8:15], v[32:39], v[88:91]
	v_mfma_f32_16x16x128_f8f6f4 v[76:79], v[0:7], v[48:55], v[76:79]
	v_mfma_f32_16x16x128_f8f6f4 v[72:75], v[8:15], v[48:55], v[72:75]
	v_mfma_f32_16x16x128_f8f6f4 v[60:63], v[0:7], v[180:187], v[212:215]
	v_mfma_f32_16x16x128_f8f6f4 v[56:59], v[8:15], v[180:187], v[216:219]
	v_mfma_f32_16x16x128_f8f6f4 v[44:47], v[0:7], v[188:195], v[220:223]
	v_mfma_f32_16x16x128_f8f6f4 v[40:43], v[8:15], v[188:195], v[224:227]
	v_mfma_f32_16x16x128_f8f6f4 v[84:87], v[16:23], v[32:39], v[84:87]
	v_mfma_f32_16x16x128_f8f6f4 v[80:83], v[24:31], v[32:39], v[80:83]
	v_mfma_f32_16x16x128_f8f6f4 v[68:71], v[16:23], v[48:55], v[68:71]
	v_mfma_f32_16x16x128_f8f6f4 v[64:67], v[24:31], v[48:55], v[64:67]
	v_mfma_f32_16x16x128_f8f6f4 v[52:55], v[16:23], v[180:187], v[228:231]
	v_mfma_f32_16x16x128_f8f6f4 v[48:51], v[24:31], v[180:187], v[196:199]
	v_mfma_f32_16x16x128_f8f6f4 v[36:39], v[16:23], v[188:195], v[200:203]
	v_mfma_f32_16x16x128_f8f6f4 v[32:35], v[24:31], v[188:195], v[204:207]
	s_setprio 0
	s_barrier
	s_add_i32 s57, s57, 2
	s_cmp_gt_u32 s57, 5
	s_cbranch_scc1 .LBB0_1253
	s_mov_b64 s[22:23], s[24:25]
	s_branch .LBB0_1248

.LBB0_1323:
	s_lshl_b32 s48, s43, 8
	s_or_b32 s49, s48, 0x80
	s_add_u32 s50, s18, 0x100
	s_addc_u32 s51, s19, 0
	s_mov_b32 s52, -2
	s_mov_b64 s[18:19], 0
	ds_read_b128 v[16:19], v175
	ds_read_b128 v[20:23], v175 offset:1024
	ds_read_b128 v[24:27], v175 offset:2048
	ds_read_b128 v[28:31], v175 offset:3072
	ds_read_b128 v[0:3], v176
	ds_read_b128 v[4:7], v176 offset:1024
	ds_read_b128 v[8:11], v176 offset:2048
	ds_read_b128 v[12:15], v176 offset:3072
	s_cmp_eq_u32 s52, 18
	s_cselect_b64 s[22:23], -1, 0
	s_add_u32 s20, s38, s18
	s_addc_u32 s21, s39, s19
	s_mov_b32 m0, s40
	ds_read_b128 v[178:181], v177
	ds_read_b128 v[182:185], v177 offset:1024
	ds_read_b128 v[186:189], v177 offset:2048
	ds_read_b128 v[190:193], v177 offset:3072
	ds_read_b128 v[194:197], v177 offset:4096
	ds_read_b128 v[198:201], v177 offset:5120
	ds_read_b128 v[202:205], v177 offset:6144
	ds_read_b128 v[206:209], v177 offset:7168
	global_load_lds_dwordx4 v166, s[20:21]
	s_mov_b32 m0, s41
	s_nop 0
	global_load_lds_dwordx4 v170, s[20:21]
	s_waitcnt vmcnt(8)
	s_waitcnt lgkmcnt(0)
	s_barrier
	s_setprio 1
	s_waitcnt lgkmcnt(0)
	v_mfma_f32_16x16x128_f8f6f4 v[156:159], v[16:23], v[178:185], 0
	v_mfma_f32_16x16x128_f8f6f4 v[152:155], v[24:31], v[178:185], 0
	v_mfma_f32_16x16x128_f8f6f4 v[140:143], v[16:23], v[186:193], 0
	v_mfma_f32_16x16x128_f8f6f4 v[136:139], v[24:31], v[186:193], 0
	v_mfma_f32_16x16x128_f8f6f4 v[124:127], v[16:23], v[194:201], 0
	v_mfma_f32_16x16x128_f8f6f4 v[120:123], v[24:31], v[194:201], 0
	v_mfma_f32_16x16x128_f8f6f4 v[108:111], v[16:23], v[202:209], 0
	v_mfma_f32_16x16x128_f8f6f4 v[104:107], v[24:31], v[202:209], 0
	v_mfma_f32_16x16x128_f8f6f4 v[148:151], v[0:7], v[178:185], 0
	v_mfma_f32_16x16x128_f8f6f4 v[144:147], v[8:15], v[178:185], 0
	v_mfma_f32_16x16x128_f8f6f4 v[132:135], v[0:7], v[186:193], 0
	v_mfma_f32_16x16x128_f8f6f4 v[128:131], v[8:15], v[186:193], 0
	v_mfma_f32_16x16x128_f8f6f4 v[116:119], v[0:7], v[194:201], 0
	v_mfma_f32_16x16x128_f8f6f4 v[112:115], v[8:15], v[194:201], 0
	v_mfma_f32_16x16x128_f8f6f4 v[100:103], v[0:7], v[202:209], 0
	v_mfma_f32_16x16x128_f8f6f4 v[96:99], v[8:15], v[202:209], 0
	s_setprio 0
	s_barrier
	s_and_b64 s[20:21], s[16:17], s[22:23]
	s_andn2_b64 vcc, exec, s[20:21]
	s_cbranch_vccnz .Lpk3_LBB0_1326
	s_mul_i32 s57, s48, s28
	s_mul_i32 s58, s49, s28
	v_add_u32_e32 v164, s57, v247
	v_add_u32_e32 v166, s58, v247
	v_add_u32_e32 v168, 0x2c000, v164
	v_add_u32_e32 v170, 0x2c000, v166
	s_branch .Lpk3_LBB0_1327
.Lpk3_LBB0_1326:
.Lpk3_LBB0_1327:
	s_add_u32 s20, s18, 0x100
	s_addc_u32 s21, s19, 0
	s_and_b64 s[56:57], s[22:23], exec
	s_cselect_b32 s4, 0, s20
	s_add_u32 s53, s50, s18
	s_addc_u32 s56, s51, s19
	s_and_b64 s[18:19], s[22:23], exec
	s_cselect_b32 s19, s15, s56
	s_cselect_b32 s18, s14, s53
	s_add_u32 s98, s2, s4
	s_addc_u32 s99, s3, s5
	s_mov_b32 m0, s26
	s_add_u32 s22, s18, 0x58000
	ds_read_b128 v[178:181], v177 offset:16384
	ds_read_b128 v[182:185], v177 offset:17408
	ds_read_b128 v[186:189], v177 offset:18432
	ds_read_b128 v[190:193], v177 offset:19456
	ds_read_b128 v[194:197], v177 offset:20480
	ds_read_b128 v[198:201], v177 offset:21504
	ds_read_b128 v[202:205], v177 offset:22528
	ds_read_b128 v[206:209], v177 offset:23552
	global_load_lds_dwordx4 v162, s[18:19]
	s_mov_b32 m0, s27
	s_addc_u32 s23, s19, 0
	global_load_lds_dwordx4 v160, s[18:19]
	s_mov_b32 m0, s29
	s_nop 0
	global_load_lds_dwordx4 v162, s[22:23]
	s_mov_b32 m0, s30
	s_nop 0
	global_load_lds_dwordx4 v160, s[22:23]
	s_mov_b32 m0, s25
	s_nop 0
	global_load_lds_dwordx4 v164, s[98:99]
	s_mov_b32 m0, s31
	s_nop 0
	global_load_lds_dwordx4 v168, s[98:99]
	s_waitcnt vmcnt(8)
	s_waitcnt lgkmcnt(0)
	s_barrier
	s_setprio 1
	s_waitcnt lgkmcnt(0)
	v_mfma_f32_16x16x128_f8f6f4 v[92:95], v[16:23], v[178:185], 0
	v_mfma_f32_16x16x128_f8f6f4 v[88:91], v[24:31], v[178:185], 0
	v_mfma_f32_16x16x128_f8f6f4 v[76:79], v[16:23], v[186:193], 0
	v_mfma_f32_16x16x128_f8f6f4 v[72:75], v[24:31], v[186:193], 0
	v_mfma_f32_16x16x128_f8f6f4 v[210:213], v[16:23], v[194:201], 0
	v_mfma_f32_16x16x128_f8f6f4 v[214:217], v[24:31], v[194:201], 0
	v_mfma_f32_16x16x128_f8f6f4 v[218:221], v[16:23], v[202:209], 0
	v_mfma_f32_16x16x128_f8f6f4 v[222:225], v[24:31], v[202:209], 0
	v_mfma_f32_16x16x128_f8f6f4 v[84:87], v[0:7], v[178:185], 0
	v_mfma_f32_16x16x128_f8f6f4 v[80:83], v[8:15], v[178:185], 0
	v_mfma_f32_16x16x128_f8f6f4 v[68:71], v[0:7], v[186:193], 0
	v_mfma_f32_16x16x128_f8f6f4 v[64:67], v[8:15], v[186:193], 0
	v_mfma_f32_16x16x128_f8f6f4 v[226:229], v[0:7], v[194:201], 0
	v_mfma_f32_16x16x128_f8f6f4 v[194:197], v[8:15], v[194:201], 0
	v_mfma_f32_16x16x128_f8f6f4 v[198:201], v[0:7], v[202:209], 0
	v_mfma_f32_16x16x128_f8f6f4 v[202:205], v[8:15], v[202:209], 0
	s_setprio 0
	s_barrier
	s_add_i32 s22, 0, 0x18000
	s_add_i32 s23, 0, 0x1c000
	v_add_u32_e32 v12, s22, v173
	v_add_u32_e32 v28, s23, v173
	ds_read_b128 v[0:3], v12
	ds_read_b128 v[4:7], v12 offset:1024
	ds_read_b128 v[8:11], v12 offset:2048
	ds_read_b128 v[12:15], v12 offset:3072
	ds_read_b128 v[16:19], v28
	ds_read_b128 v[20:23], v28 offset:1024
	ds_read_b128 v[24:27], v28 offset:2048
	ds_read_b128 v[28:31], v28 offset:3072
	s_mov_b32 m0, s34
	ds_read_b128 v[32:35], v177 offset:32768
	ds_read_b128 v[36:39], v177 offset:33792
	ds_read_b128 v[40:43], v177 offset:34816
	ds_read_b128 v[44:47], v177 offset:35840
	ds_read_b128 v[48:51], v177 offset:36864
	ds_read_b128 v[52:55], v177 offset:37888
	ds_read_b128 v[56:59], v177 offset:38912
	ds_read_b128 v[60:63], v177 offset:39936
	global_load_lds_dwordx4 v166, s[98:99]
	s_mov_b32 m0, s35
	s_nop 0
	global_load_lds_dwordx4 v170, s[98:99]
	s_waitcnt vmcnt(8)
	s_waitcnt lgkmcnt(0)
	s_barrier
	s_setprio 1
	s_waitcnt lgkmcnt(0)
	v_mfma_f32_16x16x128_f8f6f4 v[156:159], v[0:7], v[32:39], v[156:159]
	v_mfma_f32_16x16x128_f8f6f4 v[152:155], v[8:15], v[32:39], v[152:155]
	v_mfma_f32_16x16x128_f8f6f4 v[140:143], v[0:7], v[40:47], v[140:143]
	v_mfma_f32_16x16x128_f8f6f4 v[136:139], v[8:15], v[40:47], v[136:139]
	v_mfma_f32_16x16x128_f8f6f4 v[124:127], v[0:7], v[48:55], v[124:127]
	v_mfma_f32_16x16x128_f8f6f4 v[120:123], v[8:15], v[48:55], v[120:123]
	v_mfma_f32_16x16x128_f8f6f4 v[108:111], v[0:7], v[56:63], v[108:111]
	v_mfma_f32_16x16x128_f8f6f4 v[104:107], v[8:15], v[56:63], v[104:107]
	v_mfma_f32_16x16x128_f8f6f4 v[148:151], v[16:23], v[32:39], v[148:151]
	v_mfma_f32_16x16x128_f8f6f4 v[144:147], v[24:31], v[32:39], v[144:147]
	v_mfma_f32_16x16x128_f8f6f4 v[132:135], v[16:23], v[40:47], v[132:135]
	v_mfma_f32_16x16x128_f8f6f4 v[128:131], v[24:31], v[40:47], v[128:131]
	v_mfma_f32_16x16x128_f8f6f4 v[116:119], v[16:23], v[48:55], v[116:119]
	v_mfma_f32_16x16x128_f8f6f4 v[112:115], v[24:31], v[48:55], v[112:115]
	v_mfma_f32_16x16x128_f8f6f4 v[100:103], v[16:23], v[56:63], v[100:103]
	v_mfma_f32_16x16x128_f8f6f4 v[96:99], v[24:31], v[56:63], v[96:99]
	s_setprio 0
	s_barrier
	s_add_i32 s4, s22, s84
	s_add_u32 s100, s18, s10
	s_addc_u32 s101, s19, s11
	s_add_u32 s98, s98, s10
	s_addc_u32 s99, s99, s11
	s_mov_b32 m0, s4
	ds_read_b128 v[32:35], v177 offset:49152
	ds_read_b128 v[36:39], v177 offset:50176
	ds_read_b128 v[48:51], v177 offset:51200
	ds_read_b128 v[52:55], v177 offset:52224
	ds_read_b128 v[178:181], v177 offset:53248
	ds_read_b128 v[182:185], v177 offset:54272
	ds_read_b128 v[186:189], v177 offset:55296
	ds_read_b128 v[190:193], v177 offset:56320
	global_load_lds_dwordx4 v162, s[100:101]
	s_add_i32 m0, s4, 0x2000
	s_add_u32 s18, s18, 0x58080
	s_addc_u32 s19, s19, 0
	s_add_i32 s4, s23, s84
	global_load_lds_dwordx4 v160, s[100:101]
	s_mov_b32 m0, s4
	s_nop 0
	global_load_lds_dwordx4 v162, s[18:19]
	s_add_i32 m0, s4, 0x2000
	s_nop 0
	global_load_lds_dwordx4 v160, s[18:19]
	s_mov_b32 m0, s36
	s_nop 0
	global_load_lds_dwordx4 v164, s[98:99]
	s_mov_b32 m0, s37
	s_nop 0
	global_load_lds_dwordx4 v168, s[98:99]
	s_waitcnt vmcnt(8)
	s_waitcnt lgkmcnt(0)
	s_barrier
	s_setprio 1
	s_waitcnt lgkmcnt(0)
	v_mfma_f32_16x16x128_f8f6f4 v[92:95], v[0:7], v[32:39], v[92:95]
	v_mfma_f32_16x16x128_f8f6f4 v[88:91], v[8:15], v[32:39], v[88:91]
	v_mfma_f32_16x16x128_f8f6f4 v[76:79], v[0:7], v[48:55], v[76:79]
	v_mfma_f32_16x16x128_f8f6f4 v[72:75], v[8:15], v[48:55], v[72:75]
	v_mfma_f32_16x16x128_f8f6f4 v[60:63], v[0:7], v[178:185], v[210:213]
	v_mfma_f32_16x16x128_f8f6f4 v[56:59], v[8:15], v[178:185], v[214:217]
	v_mfma_f32_16x16x128_f8f6f4 v[44:47], v[0:7], v[186:193], v[218:221]
	v_mfma_f32_16x16x128_f8f6f4 v[40:43], v[8:15], v[186:193], v[222:225]
	v_mfma_f32_16x16x128_f8f6f4 v[84:87], v[16:23], v[32:39], v[84:87]
	v_mfma_f32_16x16x128_f8f6f4 v[80:83], v[24:31], v[32:39], v[80:83]
	v_mfma_f32_16x16x128_f8f6f4 v[68:71], v[16:23], v[48:55], v[68:71]
	v_mfma_f32_16x16x128_f8f6f4 v[64:67], v[24:31], v[48:55], v[64:67]
	v_mfma_f32_16x16x128_f8f6f4 v[52:55], v[16:23], v[178:185], v[226:229]
	v_mfma_f32_16x16x128_f8f6f4 v[48:51], v[24:31], v[178:185], v[194:197]
	v_mfma_f32_16x16x128_f8f6f4 v[36:39], v[16:23], v[186:193], v[198:201]
	v_mfma_f32_16x16x128_f8f6f4 v[32:35], v[24:31], v[186:193], v[202:205]
	s_setprio 0
	s_barrier
	s_add_i32 s52, s52, 2
	s_cmp_gt_u32 s52, 19
	s_cbranch_scc1 .LBB0_1329
	s_mov_b64 s[18:19], s[20:21]
	s_branch .LBB0_1324
.LBB0_1324:
	ds_read_b128 v[16:19], v175
	ds_read_b128 v[20:23], v175 offset:1024
	ds_read_b128 v[24:27], v175 offset:2048
	ds_read_b128 v[28:31], v175 offset:3072
	ds_read_b128 v[0:3], v176
	ds_read_b128 v[4:7], v176 offset:1024
	ds_read_b128 v[8:11], v176 offset:2048
	ds_read_b128 v[12:15], v176 offset:3072
	s_cmp_eq_u32 s52, 18
	s_cselect_b64 s[22:23], -1, 0
	s_add_u32 s20, s38, s18
	s_addc_u32 s21, s39, s19
	s_mov_b32 m0, s40
	ds_read_b128 v[178:181], v177
	ds_read_b128 v[182:185], v177 offset:1024
	ds_read_b128 v[186:189], v177 offset:2048
	ds_read_b128 v[190:193], v177 offset:3072
	ds_read_b128 v[194:197], v177 offset:4096
	ds_read_b128 v[198:201], v177 offset:5120
	ds_read_b128 v[202:205], v177 offset:6144
	ds_read_b128 v[206:209], v177 offset:7168
	global_load_lds_dwordx4 v166, s[20:21]
	s_mov_b32 m0, s41
	s_nop 0
	global_load_lds_dwordx4 v170, s[20:21]
	s_waitcnt vmcnt(8)
	s_waitcnt lgkmcnt(0)
	s_barrier
	s_setprio 1
	s_waitcnt lgkmcnt(0)
	v_mfma_f32_16x16x128_f8f6f4 v[156:159], v[16:23], v[178:185], v[156:159]
	v_mfma_f32_16x16x128_f8f6f4 v[152:155], v[24:31], v[178:185], v[152:155]
	v_mfma_f32_16x16x128_f8f6f4 v[140:143], v[16:23], v[186:193], v[140:143]
	v_mfma_f32_16x16x128_f8f6f4 v[136:139], v[24:31], v[186:193], v[136:139]
	v_mfma_f32_16x16x128_f8f6f4 v[124:127], v[16:23], v[194:201], v[124:127]
	v_mfma_f32_16x16x128_f8f6f4 v[120:123], v[24:31], v[194:201], v[120:123]
	v_mfma_f32_16x16x128_f8f6f4 v[108:111], v[16:23], v[202:209], v[108:111]
	v_mfma_f32_16x16x128_f8f6f4 v[104:107], v[24:31], v[202:209], v[104:107]
	v_mfma_f32_16x16x128_f8f6f4 v[148:151], v[0:7], v[178:185], v[148:151]
	v_mfma_f32_16x16x128_f8f6f4 v[144:147], v[8:15], v[178:185], v[144:147]
	v_mfma_f32_16x16x128_f8f6f4 v[132:135], v[0:7], v[186:193], v[132:135]
	v_mfma_f32_16x16x128_f8f6f4 v[128:131], v[8:15], v[186:193], v[128:131]
	v_mfma_f32_16x16x128_f8f6f4 v[116:119], v[0:7], v[194:201], v[116:119]
	v_mfma_f32_16x16x128_f8f6f4 v[112:115], v[8:15], v[194:201], v[112:115]
	v_mfma_f32_16x16x128_f8f6f4 v[100:103], v[0:7], v[202:209], v[100:103]
	v_mfma_f32_16x16x128_f8f6f4 v[96:99], v[8:15], v[202:209], v[96:99]
	s_setprio 0
	s_barrier
	s_and_b64 s[20:21], s[16:17], s[22:23]
	s_andn2_b64 vcc, exec, s[20:21]
	s_cbranch_vccnz .LBB0_1326
	s_mul_i32 s57, s48, s28
	s_mul_i32 s58, s49, s28
	v_add_u32_e32 v164, s57, v247
	v_add_u32_e32 v166, s58, v247
	v_add_u32_e32 v168, 0x2c000, v164
	v_add_u32_e32 v170, 0x2c000, v166
	s_branch .LBB0_1327
.LBB0_1326:
.LBB0_1327:
	s_add_u32 s20, s18, 0x100
	s_addc_u32 s21, s19, 0
	s_and_b64 s[56:57], s[22:23], exec
	s_cselect_b32 s4, 0, s20
	s_add_u32 s53, s50, s18
	s_addc_u32 s56, s51, s19
	s_and_b64 s[18:19], s[22:23], exec
	s_cselect_b32 s19, s15, s56
	s_cselect_b32 s18, s14, s53
	s_add_u32 s98, s2, s4
	s_addc_u32 s99, s3, s5
	s_mov_b32 m0, s26
	s_add_u32 s22, s18, 0x58000
	ds_read_b128 v[178:181], v177 offset:16384
	ds_read_b128 v[182:185], v177 offset:17408
	ds_read_b128 v[186:189], v177 offset:18432
	ds_read_b128 v[190:193], v177 offset:19456
	ds_read_b128 v[194:197], v177 offset:20480
	ds_read_b128 v[198:201], v177 offset:21504
	ds_read_b128 v[202:205], v177 offset:22528
	ds_read_b128 v[206:209], v177 offset:23552
	global_load_lds_dwordx4 v162, s[18:19]
	s_mov_b32 m0, s27
	s_addc_u32 s23, s19, 0
	global_load_lds_dwordx4 v160, s[18:19]
	s_mov_b32 m0, s29
	s_nop 0
	global_load_lds_dwordx4 v162, s[22:23]
	s_mov_b32 m0, s30
	s_nop 0
	global_load_lds_dwordx4 v160, s[22:23]
	s_mov_b32 m0, s25
	s_nop 0
	global_load_lds_dwordx4 v164, s[98:99]
	s_mov_b32 m0, s31
	s_nop 0
	global_load_lds_dwordx4 v168, s[98:99]
	s_waitcnt vmcnt(8)
	s_waitcnt lgkmcnt(0)
	s_barrier
	s_setprio 1
	s_waitcnt lgkmcnt(0)
	v_mfma_f32_16x16x128_f8f6f4 v[92:95], v[16:23], v[178:185], v[92:95]
	v_mfma_f32_16x16x128_f8f6f4 v[88:91], v[24:31], v[178:185], v[88:91]
	v_mfma_f32_16x16x128_f8f6f4 v[76:79], v[16:23], v[186:193], v[76:79]
	v_mfma_f32_16x16x128_f8f6f4 v[72:75], v[24:31], v[186:193], v[72:75]
	v_mfma_f32_16x16x128_f8f6f4 v[210:213], v[16:23], v[194:201], v[60:63]
	v_mfma_f32_16x16x128_f8f6f4 v[214:217], v[24:31], v[194:201], v[56:59]
	v_mfma_f32_16x16x128_f8f6f4 v[218:221], v[16:23], v[202:209], v[44:47]
	v_mfma_f32_16x16x128_f8f6f4 v[222:225], v[24:31], v[202:209], v[40:43]
	v_mfma_f32_16x16x128_f8f6f4 v[84:87], v[0:7], v[178:185], v[84:87]
	v_mfma_f32_16x16x128_f8f6f4 v[80:83], v[8:15], v[178:185], v[80:83]
	v_mfma_f32_16x16x128_f8f6f4 v[68:71], v[0:7], v[186:193], v[68:71]
	v_mfma_f32_16x16x128_f8f6f4 v[64:67], v[8:15], v[186:193], v[64:67]
	v_mfma_f32_16x16x128_f8f6f4 v[226:229], v[0:7], v[194:201], v[52:55]
	v_mfma_f32_16x16x128_f8f6f4 v[194:197], v[8:15], v[194:201], v[48:51]
	v_mfma_f32_16x16x128_f8f6f4 v[198:201], v[0:7], v[202:209], v[36:39]
	v_mfma_f32_16x16x128_f8f6f4 v[202:205], v[8:15], v[202:209], v[32:35]
	s_setprio 0
	s_barrier
	s_add_i32 s22, 0, 0x18000
	s_add_i32 s23, 0, 0x1c000
	v_add_u32_e32 v12, s22, v173
	v_add_u32_e32 v28, s23, v173
	ds_read_b128 v[0:3], v12
	ds_read_b128 v[4:7], v12 offset:1024
	ds_read_b128 v[8:11], v12 offset:2048
	ds_read_b128 v[12:15], v12 offset:3072
	ds_read_b128 v[16:19], v28
	ds_read_b128 v[20:23], v28 offset:1024
	ds_read_b128 v[24:27], v28 offset:2048
	ds_read_b128 v[28:31], v28 offset:3072
	s_mov_b32 m0, s34
	ds_read_b128 v[32:35], v177 offset:32768
	ds_read_b128 v[36:39], v177 offset:33792
	ds_read_b128 v[40:43], v177 offset:34816
	ds_read_b128 v[44:47], v177 offset:35840
	ds_read_b128 v[48:51], v177 offset:36864
	ds_read_b128 v[52:55], v177 offset:37888
	ds_read_b128 v[56:59], v177 offset:38912
	ds_read_b128 v[60:63], v177 offset:39936
	global_load_lds_dwordx4 v166, s[98:99]
	s_mov_b32 m0, s35
	s_nop 0
	global_load_lds_dwordx4 v170, s[98:99]
	s_waitcnt vmcnt(8)
	s_waitcnt lgkmcnt(0)
	s_barrier
	s_setprio 1
	s_waitcnt lgkmcnt(0)
	v_mfma_f32_16x16x128_f8f6f4 v[156:159], v[0:7], v[32:39], v[156:159]
	v_mfma_f32_16x16x128_f8f6f4 v[152:155], v[8:15], v[32:39], v[152:155]
	v_mfma_f32_16x16x128_f8f6f4 v[140:143], v[0:7], v[40:47], v[140:143]
	v_mfma_f32_16x16x128_f8f6f4 v[136:139], v[8:15], v[40:47], v[136:139]
	v_mfma_f32_16x16x128_f8f6f4 v[124:127], v[0:7], v[48:55], v[124:127]
	v_mfma_f32_16x16x128_f8f6f4 v[120:123], v[8:15], v[48:55], v[120:123]
	v_mfma_f32_16x16x128_f8f6f4 v[108:111], v[0:7], v[56:63], v[108:111]
	v_mfma_f32_16x16x128_f8f6f4 v[104:107], v[8:15], v[56:63], v[104:107]
	v_mfma_f32_16x16x128_f8f6f4 v[148:151], v[16:23], v[32:39], v[148:151]
	v_mfma_f32_16x16x128_f8f6f4 v[144:147], v[24:31], v[32:39], v[144:147]
	v_mfma_f32_16x16x128_f8f6f4 v[132:135], v[16:23], v[40:47], v[132:135]
	v_mfma_f32_16x16x128_f8f6f4 v[128:131], v[24:31], v[40:47], v[128:131]
	v_mfma_f32_16x16x128_f8f6f4 v[116:119], v[16:23], v[48:55], v[116:119]
	v_mfma_f32_16x16x128_f8f6f4 v[112:115], v[24:31], v[48:55], v[112:115]
	v_mfma_f32_16x16x128_f8f6f4 v[100:103], v[16:23], v[56:63], v[100:103]
	v_mfma_f32_16x16x128_f8f6f4 v[96:99], v[24:31], v[56:63], v[96:99]
	s_setprio 0
	s_barrier
	s_add_i32 s4, s22, s84
	s_add_u32 s100, s18, s10
	s_addc_u32 s101, s19, s11
	s_add_u32 s98, s98, s10
	s_addc_u32 s99, s99, s11
	s_mov_b32 m0, s4
	ds_read_b128 v[32:35], v177 offset:49152
	ds_read_b128 v[36:39], v177 offset:50176
	ds_read_b128 v[48:51], v177 offset:51200
	ds_read_b128 v[52:55], v177 offset:52224
	ds_read_b128 v[178:181], v177 offset:53248
	ds_read_b128 v[182:185], v177 offset:54272
	ds_read_b128 v[186:189], v177 offset:55296
	ds_read_b128 v[190:193], v177 offset:56320
	global_load_lds_dwordx4 v162, s[100:101]
	s_add_i32 m0, s4, 0x2000
	s_add_u32 s18, s18, 0x58080
	s_addc_u32 s19, s19, 0
	s_add_i32 s4, s23, s84
	global_load_lds_dwordx4 v160, s[100:101]
	s_mov_b32 m0, s4
	s_nop 0
	global_load_lds_dwordx4 v162, s[18:19]
	s_add_i32 m0, s4, 0x2000
	s_nop 0
	global_load_lds_dwordx4 v160, s[18:19]
	s_mov_b32 m0, s36
	s_nop 0
	global_load_lds_dwordx4 v164, s[98:99]
	s_mov_b32 m0, s37
	s_nop 0
	global_load_lds_dwordx4 v168, s[98:99]
	s_waitcnt vmcnt(8)
	s_waitcnt lgkmcnt(0)
	s_barrier
	s_setprio 1
	s_waitcnt lgkmcnt(0)
	v_mfma_f32_16x16x128_f8f6f4 v[92:95], v[0:7], v[32:39], v[92:95]
	v_mfma_f32_16x16x128_f8f6f4 v[88:91], v[8:15], v[32:39], v[88:91]
	v_mfma_f32_16x16x128_f8f6f4 v[76:79], v[0:7], v[48:55], v[76:79]
	v_mfma_f32_16x16x128_f8f6f4 v[72:75], v[8:15], v[48:55], v[72:75]
	v_mfma_f32_16x16x128_f8f6f4 v[60:63], v[0:7], v[178:185], v[210:213]
	v_mfma_f32_16x16x128_f8f6f4 v[56:59], v[8:15], v[178:185], v[214:217]
	v_mfma_f32_16x16x128_f8f6f4 v[44:47], v[0:7], v[186:193], v[218:221]
	v_mfma_f32_16x16x128_f8f6f4 v[40:43], v[8:15], v[186:193], v[222:225]
	v_mfma_f32_16x16x128_f8f6f4 v[84:87], v[16:23], v[32:39], v[84:87]
	v_mfma_f32_16x16x128_f8f6f4 v[80:83], v[24:31], v[32:39], v[80:83]
	v_mfma_f32_16x16x128_f8f6f4 v[68:71], v[16:23], v[48:55], v[68:71]
	v_mfma_f32_16x16x128_f8f6f4 v[64:67], v[24:31], v[48:55], v[64:67]
	v_mfma_f32_16x16x128_f8f6f4 v[52:55], v[16:23], v[178:185], v[226:229]
	v_mfma_f32_16x16x128_f8f6f4 v[48:51], v[24:31], v[178:185], v[194:197]
	v_mfma_f32_16x16x128_f8f6f4 v[36:39], v[16:23], v[186:193], v[198:201]
	v_mfma_f32_16x16x128_f8f6f4 v[32:35], v[24:31], v[186:193], v[202:205]
	s_setprio 0
	s_barrier
	s_add_i32 s52, s52, 2
	s_cmp_gt_u32 s52, 19
	s_cbranch_scc1 .LBB0_1329
	s_mov_b64 s[18:19], s[20:21]
	s_branch .LBB0_1324
